# norm1 and norm2 phases hand-written: each load instruction reads one contiguous 1 KB quarter of a row; 8-byte bf16 stores
# speedup vs baseline: 1.0208x; 1.0007x over previous
; __device__ __forceinline__ int ltid() { return launder((int)threadIdx.x); }
; __device__ __forceinline__ void norm_phase(const float* H, const float* g, bf16_t* HN) {
;   const int lane = ltid() & 63, gw = blockIdx.x * 8 + (ltid() >> 6), nw = gridDim.x * 8;
;   f32x4 gv[4];
; #pragma unroll
;   for (int i = 0; i < 4; ++i) gv[i] = *(const f32x4*)(g + lane * 8 + 512 * (i >> 1) + 4 * (i & 1));
;   for (int row = gw; row < NREAL + 64; row += 2 * nw) {
;     const int row2 = row + nw < NREAL + 64 ? row + nw : row;
;     const float* p = H + (size_t)row * DM + lane * 8; const float* p2 = H + (size_t)row2 * DM + lane * 8; f32x4 v[4], u[4]; float ss = 0.f, ss2 = 0.f;
; #pragma unroll
;     for (int i = 0; i < 4; ++i) { v[i] = *(const f32x4*)(p + 512 * (i >> 1) + 4 * (i & 1)); u[i] = *(const f32x4*)(p2 + 512 * (i >> 1) + 4 * (i & 1)); }
; #pragma unroll
.LBB0_221:
	s_andn2_b64 vcc, exec, s[2:3]
	s_cbranch_vccnz .LBB0_236
	v_mov_b32_e32 v0, v155
	v_mov_b32_e32 v2, v155
	v_readlane_b32 s0, v253, 56
	v_ashrrev_i32_e32 v2, 6, v2
	s_nop 0
	v_add_u32_e32 v22, s0, v2
	v_cmp_gt_i32_e32 vcc, s49, v22
	s_and_saveexec_b64 s[4:5], vcc
	v_readlane_b32 s8, v253, 59
	s_cbranch_execz .LBB0_225
	v_lshlrev_b32_e32 v0, 2, v0
	v_and_b32_e32 v0, 0xfc, v0
	v_readlane_b32 s0, v254, 2
	v_lshlrev_b32_e32 v18, 2, v0
	v_readlane_b32 s1, v254, 3
	s_nop 4
	global_load_dwordx4 v[2:5], v18, s[0:1]
	global_load_dwordx4 v[6:9], v18, s[0:1] offset:1024
	global_load_dwordx4 v[10:13], v18, s[0:1] offset:2048
	global_load_dwordx4 v[14:17], v18, s[0:1] offset:3072
	v_readlane_b32 s0, v253, 60
	v_mov_b32_e32 v19, v1
	v_readlane_b32 s1, v253, 61
	v_lshlrev_b32_e32 v20, 1, v0
	v_mov_b32_e32 v21, v1
	v_lshl_add_u64 v[18:19], s[0:1], 0, v[18:19]
	v_readlane_b32 s0, v253, 62
	v_readlane_b32 s1, v253, 63
	s_mov_b64 s[6:7], 0
	s_nop 0
	v_lshl_add_u64 v[20:21], s[0:1], 0, v[20:21]
.LBB0_224:
	v_readfirstlane_b32 s0, v22
	s_nop 3
	s_add_i32 s11, s0, s8
	s_cmp_lt_i32 s11, s49
	s_cselect_b32 s11, s11, s0
	s_lshl_b32 s12, s0, 12
	s_lshl_b32 s13, s11, 12
	v_mov_b32_e32 v68, s12
	v_mov_b32_e32 v69, 0
	v_lshl_add_u64 v[64:65], v[18:19], 0, v[68:69]
	v_mov_b32_e32 v68, s13
	v_lshl_add_u64 v[66:67], v[18:19], 0, v[68:69]
	global_load_dwordx4 v[26:29], v[64:65], off
	global_load_dwordx4 v[30:33], v[64:65], off offset:1024
	global_load_dwordx4 v[34:37], v[64:65], off offset:2048
	global_load_dwordx4 v[38:41], v[64:65], off offset:3072
	global_load_dwordx4 v[42:45], v[66:67], off
	global_load_dwordx4 v[46:49], v[66:67], off offset:1024
	global_load_dwordx4 v[50:53], v[66:67], off offset:2048
	global_load_dwordx4 v[54:57], v[66:67], off offset:3072
	s_lshl_b32 s12, s0, 11
	s_lshl_b32 s13, s11, 11
	v_mov_b32_e32 v68, s12
	v_lshl_add_u64 v[24:25], v[20:21], 0, v[68:69]
	v_mov_b32_e32 v68, s13
	v_lshl_add_u64 v[58:59], v[20:21], 0, v[68:69]
	s_lshl_b32 s9, s8, 1
	s_add_i32 s1, s0, s9
	s_cmp_lt_i32 s1, s49
	s_cbranch_scc0 .Ln1_lastA_first
	s_add_i32 s11, s1, s8
	s_cmp_lt_i32 s11, s49
	s_cselect_b32 s11, s11, s1
	s_lshl_b32 s12, s1, 12
	s_lshl_b32 s13, s11, 12
	v_mov_b32_e32 v68, s12
	v_mov_b32_e32 v69, 0
	v_lshl_add_u64 v[64:65], v[18:19], 0, v[68:69]
	v_mov_b32_e32 v68, s13
	v_lshl_add_u64 v[66:67], v[18:19], 0, v[68:69]
	global_load_dwordx4 v[88:91], v[64:65], off
	global_load_dwordx4 v[92:95], v[64:65], off offset:1024
	global_load_dwordx4 v[96:99], v[64:65], off offset:2048
	global_load_dwordx4 v[100:103], v[64:65], off offset:3072
	global_load_dwordx4 v[128:131], v[66:67], off
	global_load_dwordx4 v[132:135], v[66:67], off offset:1024
	global_load_dwordx4 v[136:139], v[66:67], off offset:2048
	global_load_dwordx4 v[140:143], v[66:67], off offset:3072
	s_lshl_b32 s12, s1, 11
	s_lshl_b32 s13, s11, 11
	v_mov_b32_e32 v68, s12
	v_lshl_add_u64 v[144:145], v[20:21], 0, v[68:69]
	v_mov_b32_e32 v68, s13
	v_lshl_add_u64 v[146:147], v[20:21], 0, v[68:69]
	s_waitcnt vmcnt(8)
	v_mul_f32_e32 v60, v26, v26
	v_fmac_f32_e32 v60, v27, v27
	v_fmac_f32_e32 v60, v28, v28
	v_fmac_f32_e32 v60, v29, v29
	v_fmac_f32_e32 v60, v30, v30
	v_fmac_f32_e32 v60, v31, v31
	v_fmac_f32_e32 v60, v32, v32
	v_fmac_f32_e32 v60, v33, v33
	v_fmac_f32_e32 v60, v34, v34
	v_fmac_f32_e32 v60, v35, v35
	v_fmac_f32_e32 v60, v36, v36
	v_fmac_f32_e32 v60, v37, v37
	v_fmac_f32_e32 v60, v38, v38
	v_fmac_f32_e32 v60, v39, v39
	v_fmac_f32_e32 v60, v40, v40
	v_fmac_f32_e32 v60, v41, v41
	v_mul_f32_e32 v61, v42, v42
	v_fmac_f32_e32 v61, v43, v43
	v_fmac_f32_e32 v61, v44, v44
	v_fmac_f32_e32 v61, v45, v45
	v_fmac_f32_e32 v61, v46, v46
	v_fmac_f32_e32 v61, v47, v47
	v_fmac_f32_e32 v61, v48, v48
	v_fmac_f32_e32 v61, v49, v49
	v_fmac_f32_e32 v61, v50, v50
	v_fmac_f32_e32 v61, v51, v51
	v_fmac_f32_e32 v61, v52, v52
	v_fmac_f32_e32 v61, v53, v53
	v_fmac_f32_e32 v61, v54, v54
	v_fmac_f32_e32 v61, v55, v55
	v_fmac_f32_e32 v61, v56, v56
	v_fmac_f32_e32 v61, v57, v57
	v_lshlrev_b32_e32 v70, 2, v210
	v_xor_b32_e32 v70, 0x80, v70
	ds_swizzle_b32 v63, v61 offset:swizzle(SWAP,16)
	ds_swizzle_b32 v62, v60 offset:swizzle(SWAP,16)
	s_waitcnt lgkmcnt(0)
	v_pk_add_f32 v[60:61], v[60:61], v[62:63]
	ds_swizzle_b32 v63, v61 offset:swizzle(SWAP,8)
	ds_swizzle_b32 v62, v60 offset:swizzle(SWAP,8)
	s_waitcnt lgkmcnt(0)
	v_pk_add_f32 v[60:61], v[60:61], v[62:63]
	ds_swizzle_b32 v63, v61 offset:swizzle(SWAP,4)
	ds_swizzle_b32 v62, v60 offset:swizzle(SWAP,4)
	s_waitcnt lgkmcnt(0)
	v_pk_add_f32 v[60:61], v[60:61], v[62:63]
	ds_swizzle_b32 v63, v61 offset:swizzle(SWAP,2)
	ds_swizzle_b32 v62, v60 offset:swizzle(SWAP,2)
	s_waitcnt lgkmcnt(0)
	v_pk_add_f32 v[60:61], v[60:61], v[62:63]
	ds_swizzle_b32 v63, v61 offset:swizzle(SWAP,1)
	ds_swizzle_b32 v62, v60 offset:swizzle(SWAP,1)
	s_waitcnt lgkmcnt(0)
	v_pk_add_f32 v[60:61], v[60:61], v[62:63]
	ds_bpermute_b32 v63, v70, v61
	ds_bpermute_b32 v62, v70, v60
	s_waitcnt lgkmcnt(0)
; __device__ __forceinline__ void store8bf(bf16_t* p, f32x4 v0, f32x4 v1) { u32x4 w; w.x = cvt_pk_bf16(v0[0], v0[1]); w.y = cvt_pk_bf16(v0[2], v0[3]); w.z = cvt_pk_bf16(v1[0], v1[1]); w.w = cvt_pk_bf16(v1[2], v1[3]); *(u32x4*)p = w; }
; __device__ __forceinline__ void norm_phase(const float* H, const float* g, bf16_t* HN) {
;     ...
;   for (int row = gw; row < NREAL + 64; row += 2 * nw) {
;     const int row2 = row + nw < NREAL + 64 ? row + nw : row;
;     const float* p = H + (size_t)row * DM + lane * 8; const float* p2 = H + (size_t)row2 * DM + lane * 8; f32x4 v[4], u[4]; float ss = 0.f, ss2 = 0.f;
; #pragma unroll
;     for (int i = 0; i < 4; ++i) { v[i] = *(const f32x4*)(p + 512 * (i >> 1) + 4 * (i & 1)); u[i] = *(const f32x4*)(p2 + 512 * (i >> 1) + 4 * (i & 1)); }
; #pragma unroll
;     for (int i = 0; i < 4; ++i) { ss += v[i][0] * v[i][0] + v[i][1] * v[i][1] + v[i][2] * v[i][2] + v[i][3] * v[i][3]; ss2 += u[i][0] * u[i][0] + u[i][1] * u[i][1] + u[i][2] * u[i][2] + u[i][3] * u[i][3]; }
;     ss = wave_sum(ss); ss2 = wave_sum(ss2); const float rs = rsqrtf(ss * (1.0f / 1024.0f) + 1e-6f), rs2 = rsqrtf(ss2 * (1.0f / 1024.0f) + 1e-6f);
;     bf16_t* q = HN + (size_t)row * DM + lane * 8; bf16_t* q2 = HN + (size_t)row2 * DM + lane * 8;
; #pragma unroll
;     for (int i = 0; i < 2; ++i) { store8bf(q + 512 * i, v[2 * i] * rs * gv[2 * i], v[2 * i + 1] * rs * gv[2 * i + 1]); store8bf(q2 + 512 * i, u[2 * i] * rs2 * gv[2 * i], u[2 * i + 1] * rs2 * gv[2 * i + 1]); }
	v_pk_add_f32 v[60:61], v[60:61], v[62:63]
	s_nop 0
	v_pk_fma_f32 v[60:61], v[60:61], s[58:59], v[154:155] op_sel_hi:[1,0,0]
	s_nop 0
	v_rsq_f32_e32 v60, v60
	v_rsq_f32_e32 v62, v61
	s_nop 0
	v_pk_mul_f32 v[26:27], v[26:27], v[60:61] op_sel_hi:[1,0]
	v_pk_mul_f32 v[26:27], v[2:3], v[26:27]
	v_pk_mul_f32 v[28:29], v[28:29], v[60:61] op_sel_hi:[1,0]
	v_pk_mul_f32 v[28:29], v[4:5], v[28:29]
	v_pk_mul_f32 v[30:31], v[30:31], v[60:61] op_sel_hi:[1,0]
	v_pk_mul_f32 v[30:31], v[6:7], v[30:31]
	v_pk_mul_f32 v[32:33], v[32:33], v[60:61] op_sel_hi:[1,0]
	v_pk_mul_f32 v[32:33], v[8:9], v[32:33]
	v_pk_mul_f32 v[34:35], v[34:35], v[60:61] op_sel_hi:[1,0]
	v_pk_mul_f32 v[34:35], v[10:11], v[34:35]
	v_pk_mul_f32 v[36:37], v[36:37], v[60:61] op_sel_hi:[1,0]
	v_pk_mul_f32 v[36:37], v[12:13], v[36:37]
	v_pk_mul_f32 v[38:39], v[38:39], v[60:61] op_sel_hi:[1,0]
	v_pk_mul_f32 v[38:39], v[14:15], v[38:39]
	v_pk_mul_f32 v[40:41], v[40:41], v[60:61] op_sel_hi:[1,0]
	v_pk_mul_f32 v[40:41], v[16:17], v[40:41]
	v_pk_mul_f32 v[42:43], v[42:43], v[62:63] op_sel_hi:[1,0]
	v_pk_mul_f32 v[42:43], v[2:3], v[42:43]
	v_pk_mul_f32 v[44:45], v[44:45], v[62:63] op_sel_hi:[1,0]
	v_pk_mul_f32 v[44:45], v[4:5], v[44:45]
	v_pk_mul_f32 v[46:47], v[46:47], v[62:63] op_sel_hi:[1,0]
	v_pk_mul_f32 v[46:47], v[6:7], v[46:47]
	v_pk_mul_f32 v[48:49], v[48:49], v[62:63] op_sel_hi:[1,0]
	v_pk_mul_f32 v[48:49], v[8:9], v[48:49]
	v_pk_mul_f32 v[50:51], v[50:51], v[62:63] op_sel_hi:[1,0]
	v_pk_mul_f32 v[50:51], v[10:11], v[50:51]
	v_pk_mul_f32 v[52:53], v[52:53], v[62:63] op_sel_hi:[1,0]
	v_pk_mul_f32 v[52:53], v[12:13], v[52:53]
	v_pk_mul_f32 v[54:55], v[54:55], v[62:63] op_sel_hi:[1,0]
	v_pk_mul_f32 v[54:55], v[14:15], v[54:55]
	v_pk_mul_f32 v[56:57], v[56:57], v[62:63] op_sel_hi:[1,0]
	v_pk_mul_f32 v[56:57], v[16:17], v[56:57]
	v_cvt_pk_bf16_f32 v26, v26, v27
	v_cvt_pk_bf16_f32 v27, v28, v29
	v_cvt_pk_bf16_f32 v30, v30, v31
	v_cvt_pk_bf16_f32 v31, v32, v33
	v_cvt_pk_bf16_f32 v34, v34, v35
	v_cvt_pk_bf16_f32 v35, v36, v37
	v_cvt_pk_bf16_f32 v38, v38, v39
	v_cvt_pk_bf16_f32 v39, v40, v41
	global_store_dwordx2 v[24:25], v[26:27], off
	global_store_dwordx2 v[24:25], v[30:31], off offset:512
	global_store_dwordx2 v[24:25], v[34:35], off offset:1024
	global_store_dwordx2 v[24:25], v[38:39], off offset:1536
	v_cvt_pk_bf16_f32 v42, v42, v43
	v_cvt_pk_bf16_f32 v43, v44, v45
	v_cvt_pk_bf16_f32 v46, v46, v47
	v_cvt_pk_bf16_f32 v47, v48, v49
	v_cvt_pk_bf16_f32 v50, v50, v51
	v_cvt_pk_bf16_f32 v51, v52, v53
	v_cvt_pk_bf16_f32 v54, v54, v55
	v_cvt_pk_bf16_f32 v55, v56, v57
	global_store_dwordx2 v[58:59], v[42:43], off
	global_store_dwordx2 v[58:59], v[46:47], off offset:512
	global_store_dwordx2 v[58:59], v[50:51], off offset:1024
	global_store_dwordx2 v[58:59], v[54:55], off offset:1536
.Ln1_loop:
	s_add_i32 s0, s1, s9
	s_cmp_lt_i32 s0, s49
	s_cbranch_scc0 .Ln1_lastB
	s_add_i32 s11, s0, s8
	s_cmp_lt_i32 s11, s49
	s_cselect_b32 s11, s11, s0
	s_lshl_b32 s12, s0, 12
	s_lshl_b32 s13, s11, 12
	v_mov_b32_e32 v68, s12
	v_mov_b32_e32 v69, 0
	v_lshl_add_u64 v[64:65], v[18:19], 0, v[68:69]
	v_mov_b32_e32 v68, s13
	v_lshl_add_u64 v[66:67], v[18:19], 0, v[68:69]
	global_load_dwordx4 v[26:29], v[64:65], off
	global_load_dwordx4 v[30:33], v[64:65], off offset:1024
	global_load_dwordx4 v[34:37], v[64:65], off offset:2048
	global_load_dwordx4 v[38:41], v[64:65], off offset:3072
	global_load_dwordx4 v[42:45], v[66:67], off
	global_load_dwordx4 v[46:49], v[66:67], off offset:1024
	global_load_dwordx4 v[50:53], v[66:67], off offset:2048
	global_load_dwordx4 v[54:57], v[66:67], off offset:3072
	s_lshl_b32 s12, s0, 11
	s_lshl_b32 s13, s11, 11
	v_mov_b32_e32 v68, s12
	v_lshl_add_u64 v[24:25], v[20:21], 0, v[68:69]
	v_mov_b32_e32 v68, s13
	v_lshl_add_u64 v[58:59], v[20:21], 0, v[68:69]
	s_waitcnt vmcnt(16)
	v_mul_f32_e32 v60, v88, v88
	v_fmac_f32_e32 v60, v89, v89
	v_fmac_f32_e32 v60, v90, v90
	v_fmac_f32_e32 v60, v91, v91
	v_fmac_f32_e32 v60, v92, v92
	v_fmac_f32_e32 v60, v93, v93
	v_fmac_f32_e32 v60, v94, v94
	v_fmac_f32_e32 v60, v95, v95
	v_fmac_f32_e32 v60, v96, v96
	v_fmac_f32_e32 v60, v97, v97
	v_fmac_f32_e32 v60, v98, v98
	v_fmac_f32_e32 v60, v99, v99
	v_fmac_f32_e32 v60, v100, v100
	v_fmac_f32_e32 v60, v101, v101
	v_fmac_f32_e32 v60, v102, v102
	v_fmac_f32_e32 v60, v103, v103
	v_mul_f32_e32 v61, v128, v128
	v_fmac_f32_e32 v61, v129, v129
	v_fmac_f32_e32 v61, v130, v130
	v_fmac_f32_e32 v61, v131, v131
	v_fmac_f32_e32 v61, v132, v132
	v_fmac_f32_e32 v61, v133, v133
	v_fmac_f32_e32 v61, v134, v134
	v_fmac_f32_e32 v61, v135, v135
	v_fmac_f32_e32 v61, v136, v136
	v_fmac_f32_e32 v61, v137, v137
	v_fmac_f32_e32 v61, v138, v138
	v_fmac_f32_e32 v61, v139, v139
	v_fmac_f32_e32 v61, v140, v140
	v_fmac_f32_e32 v61, v141, v141
	v_fmac_f32_e32 v61, v142, v142
	v_fmac_f32_e32 v61, v143, v143
	v_lshlrev_b32_e32 v70, 2, v210
	v_xor_b32_e32 v70, 0x80, v70
	ds_swizzle_b32 v63, v61 offset:swizzle(SWAP,16)
	ds_swizzle_b32 v62, v60 offset:swizzle(SWAP,16)
	s_waitcnt lgkmcnt(0)
	v_pk_add_f32 v[60:61], v[60:61], v[62:63]
	ds_swizzle_b32 v63, v61 offset:swizzle(SWAP,8)
	ds_swizzle_b32 v62, v60 offset:swizzle(SWAP,8)
	s_waitcnt lgkmcnt(0)
	v_pk_add_f32 v[60:61], v[60:61], v[62:63]
	ds_swizzle_b32 v63, v61 offset:swizzle(SWAP,4)
	ds_swizzle_b32 v62, v60 offset:swizzle(SWAP,4)
	s_waitcnt lgkmcnt(0)
	v_pk_add_f32 v[60:61], v[60:61], v[62:63]
	ds_swizzle_b32 v63, v61 offset:swizzle(SWAP,2)
	ds_swizzle_b32 v62, v60 offset:swizzle(SWAP,2)
	s_waitcnt lgkmcnt(0)
	v_pk_add_f32 v[60:61], v[60:61], v[62:63]
	ds_swizzle_b32 v63, v61 offset:swizzle(SWAP,1)
	ds_swizzle_b32 v62, v60 offset:swizzle(SWAP,1)
	s_waitcnt lgkmcnt(0)
; __device__ __forceinline__ void store8bf(bf16_t* p, f32x4 v0, f32x4 v1) { u32x4 w; w.x = cvt_pk_bf16(v0[0], v0[1]); w.y = cvt_pk_bf16(v0[2], v0[3]); w.z = cvt_pk_bf16(v1[0], v1[1]); w.w = cvt_pk_bf16(v1[2], v1[3]); *(u32x4*)p = w; }
; __device__ __forceinline__ void norm_phase(const float* H, const float* g, bf16_t* HN) {
;     ...
;   for (int row = gw; row < NREAL + 64; row += 2 * nw) {
;     const int row2 = row + nw < NREAL + 64 ? row + nw : row;
;     const float* p = H + (size_t)row * DM + lane * 8; const float* p2 = H + (size_t)row2 * DM + lane * 8; f32x4 v[4], u[4]; float ss = 0.f, ss2 = 0.f;
; #pragma unroll
;     for (int i = 0; i < 4; ++i) { v[i] = *(const f32x4*)(p + 512 * (i >> 1) + 4 * (i & 1)); u[i] = *(const f32x4*)(p2 + 512 * (i >> 1) + 4 * (i & 1)); }
; #pragma unroll
;     for (int i = 0; i < 4; ++i) { ss += v[i][0] * v[i][0] + v[i][1] * v[i][1] + v[i][2] * v[i][2] + v[i][3] * v[i][3]; ss2 += u[i][0] * u[i][0] + u[i][1] * u[i][1] + u[i][2] * u[i][2] + u[i][3] * u[i][3]; }
;     ss = wave_sum(ss); ss2 = wave_sum(ss2); const float rs = rsqrtf(ss * (1.0f / 1024.0f) + 1e-6f), rs2 = rsqrtf(ss2 * (1.0f / 1024.0f) + 1e-6f);
;     bf16_t* q = HN + (size_t)row * DM + lane * 8; bf16_t* q2 = HN + (size_t)row2 * DM + lane * 8;
; #pragma unroll
;     for (int i = 0; i < 2; ++i) { store8bf(q + 512 * i, v[2 * i] * rs * gv[2 * i], v[2 * i + 1] * rs * gv[2 * i + 1]); store8bf(q2 + 512 * i, u[2 * i] * rs2 * gv[2 * i], u[2 * i + 1] * rs2 * gv[2 * i + 1]); }
	v_pk_add_f32 v[60:61], v[60:61], v[62:63]
	ds_bpermute_b32 v63, v70, v61
	ds_bpermute_b32 v62, v70, v60
	s_waitcnt lgkmcnt(0)
	v_pk_add_f32 v[60:61], v[60:61], v[62:63]
	s_nop 0
	v_pk_fma_f32 v[60:61], v[60:61], s[58:59], v[154:155] op_sel_hi:[1,0,0]
	s_nop 0
	v_rsq_f32_e32 v60, v60
	v_rsq_f32_e32 v62, v61
	s_nop 0
	v_pk_mul_f32 v[88:89], v[88:89], v[60:61] op_sel_hi:[1,0]
	v_pk_mul_f32 v[88:89], v[2:3], v[88:89]
	v_pk_mul_f32 v[90:91], v[90:91], v[60:61] op_sel_hi:[1,0]
	v_pk_mul_f32 v[90:91], v[4:5], v[90:91]
	v_pk_mul_f32 v[92:93], v[92:93], v[60:61] op_sel_hi:[1,0]
	v_pk_mul_f32 v[92:93], v[6:7], v[92:93]
	v_pk_mul_f32 v[94:95], v[94:95], v[60:61] op_sel_hi:[1,0]
	v_pk_mul_f32 v[94:95], v[8:9], v[94:95]
	v_pk_mul_f32 v[96:97], v[96:97], v[60:61] op_sel_hi:[1,0]
	v_pk_mul_f32 v[96:97], v[10:11], v[96:97]
	v_pk_mul_f32 v[98:99], v[98:99], v[60:61] op_sel_hi:[1,0]
	v_pk_mul_f32 v[98:99], v[12:13], v[98:99]
	v_pk_mul_f32 v[100:101], v[100:101], v[60:61] op_sel_hi:[1,0]
	v_pk_mul_f32 v[100:101], v[14:15], v[100:101]
	v_pk_mul_f32 v[102:103], v[102:103], v[60:61] op_sel_hi:[1,0]
	v_pk_mul_f32 v[102:103], v[16:17], v[102:103]
	v_pk_mul_f32 v[128:129], v[128:129], v[62:63] op_sel_hi:[1,0]
	v_pk_mul_f32 v[128:129], v[2:3], v[128:129]
	v_pk_mul_f32 v[130:131], v[130:131], v[62:63] op_sel_hi:[1,0]
	v_pk_mul_f32 v[130:131], v[4:5], v[130:131]
	v_pk_mul_f32 v[132:133], v[132:133], v[62:63] op_sel_hi:[1,0]
	v_pk_mul_f32 v[132:133], v[6:7], v[132:133]
	v_pk_mul_f32 v[134:135], v[134:135], v[62:63] op_sel_hi:[1,0]
	v_pk_mul_f32 v[134:135], v[8:9], v[134:135]
	v_pk_mul_f32 v[136:137], v[136:137], v[62:63] op_sel_hi:[1,0]
	v_pk_mul_f32 v[136:137], v[10:11], v[136:137]
	v_pk_mul_f32 v[138:139], v[138:139], v[62:63] op_sel_hi:[1,0]
	v_pk_mul_f32 v[138:139], v[12:13], v[138:139]
	v_pk_mul_f32 v[140:141], v[140:141], v[62:63] op_sel_hi:[1,0]
	v_pk_mul_f32 v[140:141], v[14:15], v[140:141]
	v_pk_mul_f32 v[142:143], v[142:143], v[62:63] op_sel_hi:[1,0]
	v_pk_mul_f32 v[142:143], v[16:17], v[142:143]
	v_cvt_pk_bf16_f32 v88, v88, v89
	v_cvt_pk_bf16_f32 v89, v90, v91
	v_cvt_pk_bf16_f32 v92, v92, v93
	v_cvt_pk_bf16_f32 v93, v94, v95
	v_cvt_pk_bf16_f32 v96, v96, v97
	v_cvt_pk_bf16_f32 v97, v98, v99
	v_cvt_pk_bf16_f32 v100, v100, v101
	v_cvt_pk_bf16_f32 v101, v102, v103
	global_store_dwordx2 v[144:145], v[88:89], off
	global_store_dwordx2 v[144:145], v[92:93], off offset:512
	global_store_dwordx2 v[144:145], v[96:97], off offset:1024
	global_store_dwordx2 v[144:145], v[100:101], off offset:1536
	v_cvt_pk_bf16_f32 v128, v128, v129
	v_cvt_pk_bf16_f32 v129, v130, v131
	v_cvt_pk_bf16_f32 v132, v132, v133
	v_cvt_pk_bf16_f32 v133, v134, v135
	v_cvt_pk_bf16_f32 v136, v136, v137
	v_cvt_pk_bf16_f32 v137, v138, v139
	v_cvt_pk_bf16_f32 v140, v140, v141
	v_cvt_pk_bf16_f32 v141, v142, v143
	global_store_dwordx2 v[146:147], v[128:129], off
	global_store_dwordx2 v[146:147], v[132:133], off offset:512
	global_store_dwordx2 v[146:147], v[136:137], off offset:1024
	global_store_dwordx2 v[146:147], v[140:141], off offset:1536
	s_add_i32 s1, s0, s9
	s_cmp_lt_i32 s1, s49
	s_cbranch_scc0 .Ln1_lastA
	s_add_i32 s11, s1, s8
	s_cmp_lt_i32 s11, s49
	s_cselect_b32 s11, s11, s1
	s_lshl_b32 s12, s1, 12
	s_lshl_b32 s13, s11, 12
	v_mov_b32_e32 v68, s12
	v_mov_b32_e32 v69, 0
	v_lshl_add_u64 v[64:65], v[18:19], 0, v[68:69]
	v_mov_b32_e32 v68, s13
	v_lshl_add_u64 v[66:67], v[18:19], 0, v[68:69]
	global_load_dwordx4 v[88:91], v[64:65], off
	global_load_dwordx4 v[92:95], v[64:65], off offset:1024
	global_load_dwordx4 v[96:99], v[64:65], off offset:2048
	global_load_dwordx4 v[100:103], v[64:65], off offset:3072
	global_load_dwordx4 v[128:131], v[66:67], off
	global_load_dwordx4 v[132:135], v[66:67], off offset:1024
	global_load_dwordx4 v[136:139], v[66:67], off offset:2048
	global_load_dwordx4 v[140:143], v[66:67], off offset:3072
	s_lshl_b32 s12, s1, 11
	s_lshl_b32 s13, s11, 11
	v_mov_b32_e32 v68, s12
	v_lshl_add_u64 v[144:145], v[20:21], 0, v[68:69]
	v_mov_b32_e32 v68, s13
	v_lshl_add_u64 v[146:147], v[20:21], 0, v[68:69]
	s_waitcnt vmcnt(16)
	v_mul_f32_e32 v60, v26, v26
	v_fmac_f32_e32 v60, v27, v27
	v_fmac_f32_e32 v60, v28, v28
	v_fmac_f32_e32 v60, v29, v29
	v_fmac_f32_e32 v60, v30, v30
	v_fmac_f32_e32 v60, v31, v31
	v_fmac_f32_e32 v60, v32, v32
	v_fmac_f32_e32 v60, v33, v33
	v_fmac_f32_e32 v60, v34, v34
	v_fmac_f32_e32 v60, v35, v35
	v_fmac_f32_e32 v60, v36, v36
	v_fmac_f32_e32 v60, v37, v37
	v_fmac_f32_e32 v60, v38, v38
	v_fmac_f32_e32 v60, v39, v39
	v_fmac_f32_e32 v60, v40, v40
	v_fmac_f32_e32 v60, v41, v41
	v_mul_f32_e32 v61, v42, v42
	v_fmac_f32_e32 v61, v43, v43
	v_fmac_f32_e32 v61, v44, v44
	v_fmac_f32_e32 v61, v45, v45
	v_fmac_f32_e32 v61, v46, v46
	v_fmac_f32_e32 v61, v47, v47
	v_fmac_f32_e32 v61, v48, v48
	v_fmac_f32_e32 v61, v49, v49
	v_fmac_f32_e32 v61, v50, v50
	v_fmac_f32_e32 v61, v51, v51
	v_fmac_f32_e32 v61, v52, v52
	v_fmac_f32_e32 v61, v53, v53
	v_fmac_f32_e32 v61, v54, v54
	v_fmac_f32_e32 v61, v55, v55
	v_fmac_f32_e32 v61, v56, v56
	v_fmac_f32_e32 v61, v57, v57
	v_lshlrev_b32_e32 v70, 2, v210
	v_xor_b32_e32 v70, 0x80, v70
	ds_swizzle_b32 v63, v61 offset:swizzle(SWAP,16)
	ds_swizzle_b32 v62, v60 offset:swizzle(SWAP,16)
	s_waitcnt lgkmcnt(0)
	v_pk_add_f32 v[60:61], v[60:61], v[62:63]
	ds_swizzle_b32 v63, v61 offset:swizzle(SWAP,8)
	ds_swizzle_b32 v62, v60 offset:swizzle(SWAP,8)
	s_waitcnt lgkmcnt(0)
	v_pk_add_f32 v[60:61], v[60:61], v[62:63]
	ds_swizzle_b32 v63, v61 offset:swizzle(SWAP,4)
	ds_swizzle_b32 v62, v60 offset:swizzle(SWAP,4)
	s_waitcnt lgkmcnt(0)
	v_pk_add_f32 v[60:61], v[60:61], v[62:63]
	ds_swizzle_b32 v63, v61 offset:swizzle(SWAP,2)
	ds_swizzle_b32 v62, v60 offset:swizzle(SWAP,2)
	s_waitcnt lgkmcnt(0)
; __device__ __forceinline__ void store8bf(bf16_t* p, f32x4 v0, f32x4 v1) { u32x4 w; w.x = cvt_pk_bf16(v0[0], v0[1]); w.y = cvt_pk_bf16(v0[2], v0[3]); w.z = cvt_pk_bf16(v1[0], v1[1]); w.w = cvt_pk_bf16(v1[2], v1[3]); *(u32x4*)p = w; }
; __device__ __forceinline__ void norm_phase(const float* H, const float* g, bf16_t* HN) {
;     ...
;   for (int row = gw; row < NREAL + 64; row += 2 * nw) {
;     const int row2 = row + nw < NREAL + 64 ? row + nw : row;
;     const float* p = H + (size_t)row * DM + lane * 8; const float* p2 = H + (size_t)row2 * DM + lane * 8; f32x4 v[4], u[4]; float ss = 0.f, ss2 = 0.f;
; #pragma unroll
;     for (int i = 0; i < 4; ++i) { v[i] = *(const f32x4*)(p + 512 * (i >> 1) + 4 * (i & 1)); u[i] = *(const f32x4*)(p2 + 512 * (i >> 1) + 4 * (i & 1)); }
; #pragma unroll
;     for (int i = 0; i < 4; ++i) { ss += v[i][0] * v[i][0] + v[i][1] * v[i][1] + v[i][2] * v[i][2] + v[i][3] * v[i][3]; ss2 += u[i][0] * u[i][0] + u[i][1] * u[i][1] + u[i][2] * u[i][2] + u[i][3] * u[i][3]; }
;     ss = wave_sum(ss); ss2 = wave_sum(ss2); const float rs = rsqrtf(ss * (1.0f / 1024.0f) + 1e-6f), rs2 = rsqrtf(ss2 * (1.0f / 1024.0f) + 1e-6f);
;     bf16_t* q = HN + (size_t)row * DM + lane * 8; bf16_t* q2 = HN + (size_t)row2 * DM + lane * 8;
; #pragma unroll
;     for (int i = 0; i < 2; ++i) { store8bf(q + 512 * i, v[2 * i] * rs * gv[2 * i], v[2 * i + 1] * rs * gv[2 * i + 1]); store8bf(q2 + 512 * i, u[2 * i] * rs2 * gv[2 * i], u[2 * i + 1] * rs2 * gv[2 * i + 1]); }
	v_pk_add_f32 v[60:61], v[60:61], v[62:63]
	ds_swizzle_b32 v63, v61 offset:swizzle(SWAP,1)
	ds_swizzle_b32 v62, v60 offset:swizzle(SWAP,1)
	s_waitcnt lgkmcnt(0)
	v_pk_add_f32 v[60:61], v[60:61], v[62:63]
	ds_bpermute_b32 v63, v70, v61
	ds_bpermute_b32 v62, v70, v60
	s_waitcnt lgkmcnt(0)
	v_pk_add_f32 v[60:61], v[60:61], v[62:63]
	s_nop 0
	v_pk_fma_f32 v[60:61], v[60:61], s[58:59], v[154:155] op_sel_hi:[1,0,0]
	s_nop 0
	v_rsq_f32_e32 v60, v60
	v_rsq_f32_e32 v62, v61
	s_nop 0
	v_pk_mul_f32 v[26:27], v[26:27], v[60:61] op_sel_hi:[1,0]
	v_pk_mul_f32 v[26:27], v[2:3], v[26:27]
	v_pk_mul_f32 v[28:29], v[28:29], v[60:61] op_sel_hi:[1,0]
	v_pk_mul_f32 v[28:29], v[4:5], v[28:29]
	v_pk_mul_f32 v[30:31], v[30:31], v[60:61] op_sel_hi:[1,0]
	v_pk_mul_f32 v[30:31], v[6:7], v[30:31]
	v_pk_mul_f32 v[32:33], v[32:33], v[60:61] op_sel_hi:[1,0]
	v_pk_mul_f32 v[32:33], v[8:9], v[32:33]
	v_pk_mul_f32 v[34:35], v[34:35], v[60:61] op_sel_hi:[1,0]
	v_pk_mul_f32 v[34:35], v[10:11], v[34:35]
	v_pk_mul_f32 v[36:37], v[36:37], v[60:61] op_sel_hi:[1,0]
	v_pk_mul_f32 v[36:37], v[12:13], v[36:37]
	v_pk_mul_f32 v[38:39], v[38:39], v[60:61] op_sel_hi:[1,0]
	v_pk_mul_f32 v[38:39], v[14:15], v[38:39]
	v_pk_mul_f32 v[40:41], v[40:41], v[60:61] op_sel_hi:[1,0]
	v_pk_mul_f32 v[40:41], v[16:17], v[40:41]
	v_pk_mul_f32 v[42:43], v[42:43], v[62:63] op_sel_hi:[1,0]
	v_pk_mul_f32 v[42:43], v[2:3], v[42:43]
	v_pk_mul_f32 v[44:45], v[44:45], v[62:63] op_sel_hi:[1,0]
	v_pk_mul_f32 v[44:45], v[4:5], v[44:45]
	v_pk_mul_f32 v[46:47], v[46:47], v[62:63] op_sel_hi:[1,0]
	v_pk_mul_f32 v[46:47], v[6:7], v[46:47]
	v_pk_mul_f32 v[48:49], v[48:49], v[62:63] op_sel_hi:[1,0]
	v_pk_mul_f32 v[48:49], v[8:9], v[48:49]
	v_pk_mul_f32 v[50:51], v[50:51], v[62:63] op_sel_hi:[1,0]
	v_pk_mul_f32 v[50:51], v[10:11], v[50:51]
	v_pk_mul_f32 v[52:53], v[52:53], v[62:63] op_sel_hi:[1,0]
	v_pk_mul_f32 v[52:53], v[12:13], v[52:53]
	v_pk_mul_f32 v[54:55], v[54:55], v[62:63] op_sel_hi:[1,0]
	v_pk_mul_f32 v[54:55], v[14:15], v[54:55]
	v_pk_mul_f32 v[56:57], v[56:57], v[62:63] op_sel_hi:[1,0]
	v_pk_mul_f32 v[56:57], v[16:17], v[56:57]
	v_cvt_pk_bf16_f32 v26, v26, v27
	v_cvt_pk_bf16_f32 v27, v28, v29
	v_cvt_pk_bf16_f32 v30, v30, v31
	v_cvt_pk_bf16_f32 v31, v32, v33
	v_cvt_pk_bf16_f32 v34, v34, v35
	v_cvt_pk_bf16_f32 v35, v36, v37
	v_cvt_pk_bf16_f32 v38, v38, v39
	v_cvt_pk_bf16_f32 v39, v40, v41
	global_store_dwordx2 v[24:25], v[26:27], off
	global_store_dwordx2 v[24:25], v[30:31], off offset:512
	global_store_dwordx2 v[24:25], v[34:35], off offset:1024
	global_store_dwordx2 v[24:25], v[38:39], off offset:1536
	v_cvt_pk_bf16_f32 v42, v42, v43
	v_cvt_pk_bf16_f32 v43, v44, v45
	v_cvt_pk_bf16_f32 v46, v46, v47
	v_cvt_pk_bf16_f32 v47, v48, v49
	v_cvt_pk_bf16_f32 v50, v50, v51
	v_cvt_pk_bf16_f32 v51, v52, v53
	v_cvt_pk_bf16_f32 v54, v54, v55
	v_cvt_pk_bf16_f32 v55, v56, v57
	global_store_dwordx2 v[58:59], v[42:43], off
	global_store_dwordx2 v[58:59], v[46:47], off offset:512
	global_store_dwordx2 v[58:59], v[50:51], off offset:1024
	global_store_dwordx2 v[58:59], v[54:55], off offset:1536
	s_branch .Ln1_loop
.Ln1_lastA_first:
	s_waitcnt vmcnt(0)
	v_mul_f32_e32 v60, v26, v26
	v_fmac_f32_e32 v60, v27, v27
	v_fmac_f32_e32 v60, v28, v28
	v_fmac_f32_e32 v60, v29, v29
	v_fmac_f32_e32 v60, v30, v30
	v_fmac_f32_e32 v60, v31, v31
	v_fmac_f32_e32 v60, v32, v32
	v_fmac_f32_e32 v60, v33, v33
	v_fmac_f32_e32 v60, v34, v34
	v_fmac_f32_e32 v60, v35, v35
	v_fmac_f32_e32 v60, v36, v36
	v_fmac_f32_e32 v60, v37, v37
	v_fmac_f32_e32 v60, v38, v38
	v_fmac_f32_e32 v60, v39, v39
	v_fmac_f32_e32 v60, v40, v40
	v_fmac_f32_e32 v60, v41, v41
	v_mul_f32_e32 v61, v42, v42
	v_fmac_f32_e32 v61, v43, v43
	v_fmac_f32_e32 v61, v44, v44
	v_fmac_f32_e32 v61, v45, v45
	v_fmac_f32_e32 v61, v46, v46
	v_fmac_f32_e32 v61, v47, v47
	v_fmac_f32_e32 v61, v48, v48
	v_fmac_f32_e32 v61, v49, v49
	v_fmac_f32_e32 v61, v50, v50
	v_fmac_f32_e32 v61, v51, v51
	v_fmac_f32_e32 v61, v52, v52
	v_fmac_f32_e32 v61, v53, v53
	v_fmac_f32_e32 v61, v54, v54
	v_fmac_f32_e32 v61, v55, v55
	v_fmac_f32_e32 v61, v56, v56
	v_fmac_f32_e32 v61, v57, v57
	v_lshlrev_b32_e32 v70, 2, v210
	v_xor_b32_e32 v70, 0x80, v70
	ds_swizzle_b32 v63, v61 offset:swizzle(SWAP,16)
	ds_swizzle_b32 v62, v60 offset:swizzle(SWAP,16)
	s_waitcnt lgkmcnt(0)
	v_pk_add_f32 v[60:61], v[60:61], v[62:63]
	ds_swizzle_b32 v63, v61 offset:swizzle(SWAP,8)
	ds_swizzle_b32 v62, v60 offset:swizzle(SWAP,8)
	s_waitcnt lgkmcnt(0)
	v_pk_add_f32 v[60:61], v[60:61], v[62:63]
	ds_swizzle_b32 v63, v61 offset:swizzle(SWAP,4)
	ds_swizzle_b32 v62, v60 offset:swizzle(SWAP,4)
	s_waitcnt lgkmcnt(0)
	v_pk_add_f32 v[60:61], v[60:61], v[62:63]
	ds_swizzle_b32 v63, v61 offset:swizzle(SWAP,2)
	ds_swizzle_b32 v62, v60 offset:swizzle(SWAP,2)
	s_waitcnt lgkmcnt(0)
	v_pk_add_f32 v[60:61], v[60:61], v[62:63]
	ds_swizzle_b32 v63, v61 offset:swizzle(SWAP,1)
	ds_swizzle_b32 v62, v60 offset:swizzle(SWAP,1)
	s_waitcnt lgkmcnt(0)
	v_pk_add_f32 v[60:61], v[60:61], v[62:63]
	ds_bpermute_b32 v63, v70, v61
	ds_bpermute_b32 v62, v70, v60
	s_waitcnt lgkmcnt(0)
; __device__ __forceinline__ void store8bf(bf16_t* p, f32x4 v0, f32x4 v1) { u32x4 w; w.x = cvt_pk_bf16(v0[0], v0[1]); w.y = cvt_pk_bf16(v0[2], v0[3]); w.z = cvt_pk_bf16(v1[0], v1[1]); w.w = cvt_pk_bf16(v1[2], v1[3]); *(u32x4*)p = w; }
; __device__ __forceinline__ void norm_phase(const float* H, const float* g, bf16_t* HN) {
;     ...
;     for (int i = 0; i < 4; ++i) { ss += v[i][0] * v[i][0] + v[i][1] * v[i][1] + v[i][2] * v[i][2] + v[i][3] * v[i][3]; ss2 += u[i][0] * u[i][0] + u[i][1] * u[i][1] + u[i][2] * u[i][2] + u[i][3] * u[i][3]; }
;     ss = wave_sum(ss); ss2 = wave_sum(ss2); const float rs = rsqrtf(ss * (1.0f / 1024.0f) + 1e-6f), rs2 = rsqrtf(ss2 * (1.0f / 1024.0f) + 1e-6f);
;     bf16_t* q = HN + (size_t)row * DM + lane * 8; bf16_t* q2 = HN + (size_t)row2 * DM + lane * 8;
; #pragma unroll
;     for (int i = 0; i < 2; ++i) { store8bf(q + 512 * i, v[2 * i] * rs * gv[2 * i], v[2 * i + 1] * rs * gv[2 * i + 1]); store8bf(q2 + 512 * i, u[2 * i] * rs2 * gv[2 * i], u[2 * i + 1] * rs2 * gv[2 * i + 1]); }
	v_pk_add_f32 v[60:61], v[60:61], v[62:63]
	s_nop 0
	v_pk_fma_f32 v[60:61], v[60:61], s[58:59], v[154:155] op_sel_hi:[1,0,0]
	s_nop 0
	v_rsq_f32_e32 v60, v60
	v_rsq_f32_e32 v62, v61
	s_nop 0
	v_pk_mul_f32 v[26:27], v[26:27], v[60:61] op_sel_hi:[1,0]
	v_pk_mul_f32 v[26:27], v[2:3], v[26:27]
	v_pk_mul_f32 v[28:29], v[28:29], v[60:61] op_sel_hi:[1,0]
	v_pk_mul_f32 v[28:29], v[4:5], v[28:29]
	v_pk_mul_f32 v[30:31], v[30:31], v[60:61] op_sel_hi:[1,0]
	v_pk_mul_f32 v[30:31], v[6:7], v[30:31]
	v_pk_mul_f32 v[32:33], v[32:33], v[60:61] op_sel_hi:[1,0]
	v_pk_mul_f32 v[32:33], v[8:9], v[32:33]
	v_pk_mul_f32 v[34:35], v[34:35], v[60:61] op_sel_hi:[1,0]
	v_pk_mul_f32 v[34:35], v[10:11], v[34:35]
	v_pk_mul_f32 v[36:37], v[36:37], v[60:61] op_sel_hi:[1,0]
	v_pk_mul_f32 v[36:37], v[12:13], v[36:37]
	v_pk_mul_f32 v[38:39], v[38:39], v[60:61] op_sel_hi:[1,0]
	v_pk_mul_f32 v[38:39], v[14:15], v[38:39]
	v_pk_mul_f32 v[40:41], v[40:41], v[60:61] op_sel_hi:[1,0]
	v_pk_mul_f32 v[40:41], v[16:17], v[40:41]
	v_pk_mul_f32 v[42:43], v[42:43], v[62:63] op_sel_hi:[1,0]
	v_pk_mul_f32 v[42:43], v[2:3], v[42:43]
	v_pk_mul_f32 v[44:45], v[44:45], v[62:63] op_sel_hi:[1,0]
	v_pk_mul_f32 v[44:45], v[4:5], v[44:45]
	v_pk_mul_f32 v[46:47], v[46:47], v[62:63] op_sel_hi:[1,0]
	v_pk_mul_f32 v[46:47], v[6:7], v[46:47]
	v_pk_mul_f32 v[48:49], v[48:49], v[62:63] op_sel_hi:[1,0]
	v_pk_mul_f32 v[48:49], v[8:9], v[48:49]
	v_pk_mul_f32 v[50:51], v[50:51], v[62:63] op_sel_hi:[1,0]
	v_pk_mul_f32 v[50:51], v[10:11], v[50:51]
	v_pk_mul_f32 v[52:53], v[52:53], v[62:63] op_sel_hi:[1,0]
	v_pk_mul_f32 v[52:53], v[12:13], v[52:53]
	v_pk_mul_f32 v[54:55], v[54:55], v[62:63] op_sel_hi:[1,0]
	v_pk_mul_f32 v[54:55], v[14:15], v[54:55]
	v_pk_mul_f32 v[56:57], v[56:57], v[62:63] op_sel_hi:[1,0]
	v_pk_mul_f32 v[56:57], v[16:17], v[56:57]
	v_cvt_pk_bf16_f32 v26, v26, v27
	v_cvt_pk_bf16_f32 v27, v28, v29
	v_cvt_pk_bf16_f32 v30, v30, v31
	v_cvt_pk_bf16_f32 v31, v32, v33
	v_cvt_pk_bf16_f32 v34, v34, v35
	v_cvt_pk_bf16_f32 v35, v36, v37
	v_cvt_pk_bf16_f32 v38, v38, v39
	v_cvt_pk_bf16_f32 v39, v40, v41
	global_store_dwordx2 v[24:25], v[26:27], off
	global_store_dwordx2 v[24:25], v[30:31], off offset:512
	global_store_dwordx2 v[24:25], v[34:35], off offset:1024
	global_store_dwordx2 v[24:25], v[38:39], off offset:1536
	v_cvt_pk_bf16_f32 v42, v42, v43
	v_cvt_pk_bf16_f32 v43, v44, v45
	v_cvt_pk_bf16_f32 v46, v46, v47
	v_cvt_pk_bf16_f32 v47, v48, v49
	v_cvt_pk_bf16_f32 v50, v50, v51
	v_cvt_pk_bf16_f32 v51, v52, v53
	v_cvt_pk_bf16_f32 v54, v54, v55
	v_cvt_pk_bf16_f32 v55, v56, v57
	global_store_dwordx2 v[58:59], v[42:43], off
	global_store_dwordx2 v[58:59], v[46:47], off offset:512
	global_store_dwordx2 v[58:59], v[50:51], off offset:1024
	global_store_dwordx2 v[58:59], v[54:55], off offset:1536
	s_branch .Ln1_done
.Ln1_lastB:
	s_waitcnt vmcnt(0)
	v_mul_f32_e32 v60, v88, v88
	v_fmac_f32_e32 v60, v89, v89
	v_fmac_f32_e32 v60, v90, v90
	v_fmac_f32_e32 v60, v91, v91
	v_fmac_f32_e32 v60, v92, v92
	v_fmac_f32_e32 v60, v93, v93
	v_fmac_f32_e32 v60, v94, v94
	v_fmac_f32_e32 v60, v95, v95
	v_fmac_f32_e32 v60, v96, v96
	v_fmac_f32_e32 v60, v97, v97
	v_fmac_f32_e32 v60, v98, v98
	v_fmac_f32_e32 v60, v99, v99
	v_fmac_f32_e32 v60, v100, v100
	v_fmac_f32_e32 v60, v101, v101
	v_fmac_f32_e32 v60, v102, v102
	v_fmac_f32_e32 v60, v103, v103
	v_mul_f32_e32 v61, v128, v128
	v_fmac_f32_e32 v61, v129, v129
	v_fmac_f32_e32 v61, v130, v130
	v_fmac_f32_e32 v61, v131, v131
	v_fmac_f32_e32 v61, v132, v132
	v_fmac_f32_e32 v61, v133, v133
	v_fmac_f32_e32 v61, v134, v134
	v_fmac_f32_e32 v61, v135, v135
	v_fmac_f32_e32 v61, v136, v136
	v_fmac_f32_e32 v61, v137, v137
	v_fmac_f32_e32 v61, v138, v138
	v_fmac_f32_e32 v61, v139, v139
	v_fmac_f32_e32 v61, v140, v140
	v_fmac_f32_e32 v61, v141, v141
	v_fmac_f32_e32 v61, v142, v142
	v_fmac_f32_e32 v61, v143, v143
	v_lshlrev_b32_e32 v70, 2, v210
	v_xor_b32_e32 v70, 0x80, v70
	ds_swizzle_b32 v63, v61 offset:swizzle(SWAP,16)
	ds_swizzle_b32 v62, v60 offset:swizzle(SWAP,16)
	s_waitcnt lgkmcnt(0)
	v_pk_add_f32 v[60:61], v[60:61], v[62:63]
	ds_swizzle_b32 v63, v61 offset:swizzle(SWAP,8)
	ds_swizzle_b32 v62, v60 offset:swizzle(SWAP,8)
	s_waitcnt lgkmcnt(0)
	v_pk_add_f32 v[60:61], v[60:61], v[62:63]
	ds_swizzle_b32 v63, v61 offset:swizzle(SWAP,4)
	ds_swizzle_b32 v62, v60 offset:swizzle(SWAP,4)
	s_waitcnt lgkmcnt(0)
	v_pk_add_f32 v[60:61], v[60:61], v[62:63]
	ds_swizzle_b32 v63, v61 offset:swizzle(SWAP,2)
	ds_swizzle_b32 v62, v60 offset:swizzle(SWAP,2)
	s_waitcnt lgkmcnt(0)
	v_pk_add_f32 v[60:61], v[60:61], v[62:63]
	ds_swizzle_b32 v63, v61 offset:swizzle(SWAP,1)
	ds_swizzle_b32 v62, v60 offset:swizzle(SWAP,1)
	s_waitcnt lgkmcnt(0)
	v_pk_add_f32 v[60:61], v[60:61], v[62:63]
	ds_bpermute_b32 v63, v70, v61
	ds_bpermute_b32 v62, v70, v60
	s_waitcnt lgkmcnt(0)
; __device__ __forceinline__ void store8bf(bf16_t* p, f32x4 v0, f32x4 v1) { u32x4 w; w.x = cvt_pk_bf16(v0[0], v0[1]); w.y = cvt_pk_bf16(v0[2], v0[3]); w.z = cvt_pk_bf16(v1[0], v1[1]); w.w = cvt_pk_bf16(v1[2], v1[3]); *(u32x4*)p = w; }
; __device__ __forceinline__ void norm_phase(const float* H, const float* g, bf16_t* HN) {
;     ...
;     for (int i = 0; i < 4; ++i) { ss += v[i][0] * v[i][0] + v[i][1] * v[i][1] + v[i][2] * v[i][2] + v[i][3] * v[i][3]; ss2 += u[i][0] * u[i][0] + u[i][1] * u[i][1] + u[i][2] * u[i][2] + u[i][3] * u[i][3]; }
;     ss = wave_sum(ss); ss2 = wave_sum(ss2); const float rs = rsqrtf(ss * (1.0f / 1024.0f) + 1e-6f), rs2 = rsqrtf(ss2 * (1.0f / 1024.0f) + 1e-6f);
;     bf16_t* q = HN + (size_t)row * DM + lane * 8; bf16_t* q2 = HN + (size_t)row2 * DM + lane * 8;
; #pragma unroll
;     for (int i = 0; i < 2; ++i) { store8bf(q + 512 * i, v[2 * i] * rs * gv[2 * i], v[2 * i + 1] * rs * gv[2 * i + 1]); store8bf(q2 + 512 * i, u[2 * i] * rs2 * gv[2 * i], u[2 * i + 1] * rs2 * gv[2 * i + 1]); }
	v_pk_add_f32 v[60:61], v[60:61], v[62:63]
	s_nop 0
	v_pk_fma_f32 v[60:61], v[60:61], s[58:59], v[154:155] op_sel_hi:[1,0,0]
	s_nop 0
	v_rsq_f32_e32 v60, v60
	v_rsq_f32_e32 v62, v61
	s_nop 0
	v_pk_mul_f32 v[88:89], v[88:89], v[60:61] op_sel_hi:[1,0]
	v_pk_mul_f32 v[88:89], v[2:3], v[88:89]
	v_pk_mul_f32 v[90:91], v[90:91], v[60:61] op_sel_hi:[1,0]
	v_pk_mul_f32 v[90:91], v[4:5], v[90:91]
	v_pk_mul_f32 v[92:93], v[92:93], v[60:61] op_sel_hi:[1,0]
	v_pk_mul_f32 v[92:93], v[6:7], v[92:93]
	v_pk_mul_f32 v[94:95], v[94:95], v[60:61] op_sel_hi:[1,0]
	v_pk_mul_f32 v[94:95], v[8:9], v[94:95]
	v_pk_mul_f32 v[96:97], v[96:97], v[60:61] op_sel_hi:[1,0]
	v_pk_mul_f32 v[96:97], v[10:11], v[96:97]
	v_pk_mul_f32 v[98:99], v[98:99], v[60:61] op_sel_hi:[1,0]
	v_pk_mul_f32 v[98:99], v[12:13], v[98:99]
	v_pk_mul_f32 v[100:101], v[100:101], v[60:61] op_sel_hi:[1,0]
	v_pk_mul_f32 v[100:101], v[14:15], v[100:101]
	v_pk_mul_f32 v[102:103], v[102:103], v[60:61] op_sel_hi:[1,0]
	v_pk_mul_f32 v[102:103], v[16:17], v[102:103]
	v_pk_mul_f32 v[128:129], v[128:129], v[62:63] op_sel_hi:[1,0]
	v_pk_mul_f32 v[128:129], v[2:3], v[128:129]
	v_pk_mul_f32 v[130:131], v[130:131], v[62:63] op_sel_hi:[1,0]
	v_pk_mul_f32 v[130:131], v[4:5], v[130:131]
	v_pk_mul_f32 v[132:133], v[132:133], v[62:63] op_sel_hi:[1,0]
	v_pk_mul_f32 v[132:133], v[6:7], v[132:133]
	v_pk_mul_f32 v[134:135], v[134:135], v[62:63] op_sel_hi:[1,0]
	v_pk_mul_f32 v[134:135], v[8:9], v[134:135]
	v_pk_mul_f32 v[136:137], v[136:137], v[62:63] op_sel_hi:[1,0]
	v_pk_mul_f32 v[136:137], v[10:11], v[136:137]
	v_pk_mul_f32 v[138:139], v[138:139], v[62:63] op_sel_hi:[1,0]
	v_pk_mul_f32 v[138:139], v[12:13], v[138:139]
	v_pk_mul_f32 v[140:141], v[140:141], v[62:63] op_sel_hi:[1,0]
	v_pk_mul_f32 v[140:141], v[14:15], v[140:141]
	v_pk_mul_f32 v[142:143], v[142:143], v[62:63] op_sel_hi:[1,0]
	v_pk_mul_f32 v[142:143], v[16:17], v[142:143]
	v_cvt_pk_bf16_f32 v88, v88, v89
	v_cvt_pk_bf16_f32 v89, v90, v91
	v_cvt_pk_bf16_f32 v92, v92, v93
	v_cvt_pk_bf16_f32 v93, v94, v95
	v_cvt_pk_bf16_f32 v96, v96, v97
	v_cvt_pk_bf16_f32 v97, v98, v99
	v_cvt_pk_bf16_f32 v100, v100, v101
	v_cvt_pk_bf16_f32 v101, v102, v103
	global_store_dwordx2 v[144:145], v[88:89], off
	global_store_dwordx2 v[144:145], v[92:93], off offset:512
	global_store_dwordx2 v[144:145], v[96:97], off offset:1024
	global_store_dwordx2 v[144:145], v[100:101], off offset:1536
	v_cvt_pk_bf16_f32 v128, v128, v129
	v_cvt_pk_bf16_f32 v129, v130, v131
	v_cvt_pk_bf16_f32 v132, v132, v133
	v_cvt_pk_bf16_f32 v133, v134, v135
	v_cvt_pk_bf16_f32 v136, v136, v137
	v_cvt_pk_bf16_f32 v137, v138, v139
	v_cvt_pk_bf16_f32 v140, v140, v141
	v_cvt_pk_bf16_f32 v141, v142, v143
	global_store_dwordx2 v[146:147], v[128:129], off
	global_store_dwordx2 v[146:147], v[132:133], off offset:512
	global_store_dwordx2 v[146:147], v[136:137], off offset:1024
	global_store_dwordx2 v[146:147], v[140:141], off offset:1536
	s_branch .Ln1_done
; __device__ __forceinline__ void store8bf(bf16_t* p, f32x4 v0, f32x4 v1) { u32x4 w; w.x = cvt_pk_bf16(v0[0], v0[1]); w.y = cvt_pk_bf16(v0[2], v0[3]); w.z = cvt_pk_bf16(v1[0], v1[1]); w.w = cvt_pk_bf16(v1[2], v1[3]); *(u32x4*)p = w; }
; __device__ __forceinline__ void norm_phase(const float* H, const float* g, bf16_t* HN) {
;     ...
;   for (int row = gw; row < NREAL + 64; row += 2 * nw) {
;     const int row2 = row + nw < NREAL + 64 ? row + nw : row;
;     const float* p = H + (size_t)row * DM + lane * 8; const float* p2 = H + (size_t)row2 * DM + lane * 8; f32x4 v[4], u[4]; float ss = 0.f, ss2 = 0.f;
; #pragma unroll
;     for (int i = 0; i < 4; ++i) { v[i] = *(const f32x4*)(p + 512 * (i >> 1) + 4 * (i & 1)); u[i] = *(const f32x4*)(p2 + 512 * (i >> 1) + 4 * (i & 1)); }
; #pragma unroll
;     for (int i = 0; i < 4; ++i) { ss += v[i][0] * v[i][0] + v[i][1] * v[i][1] + v[i][2] * v[i][2] + v[i][3] * v[i][3]; ss2 += u[i][0] * u[i][0] + u[i][1] * u[i][1] + u[i][2] * u[i][2] + u[i][3] * u[i][3]; }
;     ss = wave_sum(ss); ss2 = wave_sum(ss2); const float rs = rsqrtf(ss * (1.0f / 1024.0f) + 1e-6f), rs2 = rsqrtf(ss2 * (1.0f / 1024.0f) + 1e-6f);
;     bf16_t* q = HN + (size_t)row * DM + lane * 8; bf16_t* q2 = HN + (size_t)row2 * DM + lane * 8;
; #pragma unroll
;     for (int i = 0; i < 2; ++i) { store8bf(q + 512 * i, v[2 * i] * rs * gv[2 * i], v[2 * i + 1] * rs * gv[2 * i + 1]); store8bf(q2 + 512 * i, u[2 * i] * rs2 * gv[2 * i], u[2 * i + 1] * rs2 * gv[2 * i + 1]); }
.Ln1_lastA:
	s_waitcnt vmcnt(0)
	v_mul_f32_e32 v60, v26, v26
	v_fmac_f32_e32 v60, v27, v27
	v_fmac_f32_e32 v60, v28, v28
	v_fmac_f32_e32 v60, v29, v29
	v_fmac_f32_e32 v60, v30, v30
	v_fmac_f32_e32 v60, v31, v31
	v_fmac_f32_e32 v60, v32, v32
	v_fmac_f32_e32 v60, v33, v33
	v_fmac_f32_e32 v60, v34, v34
	v_fmac_f32_e32 v60, v35, v35
	v_fmac_f32_e32 v60, v36, v36
	v_fmac_f32_e32 v60, v37, v37
	v_fmac_f32_e32 v60, v38, v38
	v_fmac_f32_e32 v60, v39, v39
	v_fmac_f32_e32 v60, v40, v40
	v_fmac_f32_e32 v60, v41, v41
	v_mul_f32_e32 v61, v42, v42
	v_fmac_f32_e32 v61, v43, v43
	v_fmac_f32_e32 v61, v44, v44
	v_fmac_f32_e32 v61, v45, v45
	v_fmac_f32_e32 v61, v46, v46
	v_fmac_f32_e32 v61, v47, v47
	v_fmac_f32_e32 v61, v48, v48
	v_fmac_f32_e32 v61, v49, v49
	v_fmac_f32_e32 v61, v50, v50
	v_fmac_f32_e32 v61, v51, v51
	v_fmac_f32_e32 v61, v52, v52
	v_fmac_f32_e32 v61, v53, v53
	v_fmac_f32_e32 v61, v54, v54
	v_fmac_f32_e32 v61, v55, v55
	v_fmac_f32_e32 v61, v56, v56
	v_fmac_f32_e32 v61, v57, v57
	v_lshlrev_b32_e32 v70, 2, v210
	v_xor_b32_e32 v70, 0x80, v70
	ds_swizzle_b32 v63, v61 offset:swizzle(SWAP,16)
	ds_swizzle_b32 v62, v60 offset:swizzle(SWAP,16)
	s_waitcnt lgkmcnt(0)
	v_pk_add_f32 v[60:61], v[60:61], v[62:63]
	ds_swizzle_b32 v63, v61 offset:swizzle(SWAP,8)
	ds_swizzle_b32 v62, v60 offset:swizzle(SWAP,8)
	s_waitcnt lgkmcnt(0)
	v_pk_add_f32 v[60:61], v[60:61], v[62:63]
	ds_swizzle_b32 v63, v61 offset:swizzle(SWAP,4)
	ds_swizzle_b32 v62, v60 offset:swizzle(SWAP,4)
	s_waitcnt lgkmcnt(0)
	v_pk_add_f32 v[60:61], v[60:61], v[62:63]
	ds_swizzle_b32 v63, v61 offset:swizzle(SWAP,2)
	ds_swizzle_b32 v62, v60 offset:swizzle(SWAP,2)
	s_waitcnt lgkmcnt(0)
	v_pk_add_f32 v[60:61], v[60:61], v[62:63]
	ds_swizzle_b32 v63, v61 offset:swizzle(SWAP,1)
	ds_swizzle_b32 v62, v60 offset:swizzle(SWAP,1)
	s_waitcnt lgkmcnt(0)
	v_pk_add_f32 v[60:61], v[60:61], v[62:63]
	ds_bpermute_b32 v63, v70, v61
	ds_bpermute_b32 v62, v70, v60
	s_waitcnt lgkmcnt(0)
	v_pk_add_f32 v[60:61], v[60:61], v[62:63]
	s_nop 0
	v_pk_fma_f32 v[60:61], v[60:61], s[58:59], v[154:155] op_sel_hi:[1,0,0]
	s_nop 0
	v_rsq_f32_e32 v60, v60
	v_rsq_f32_e32 v62, v61
	s_nop 0
	v_pk_mul_f32 v[26:27], v[26:27], v[60:61] op_sel_hi:[1,0]
	v_pk_mul_f32 v[26:27], v[2:3], v[26:27]
	v_pk_mul_f32 v[28:29], v[28:29], v[60:61] op_sel_hi:[1,0]
	v_pk_mul_f32 v[28:29], v[4:5], v[28:29]
	v_pk_mul_f32 v[30:31], v[30:31], v[60:61] op_sel_hi:[1,0]
	v_pk_mul_f32 v[30:31], v[6:7], v[30:31]
	v_pk_mul_f32 v[32:33], v[32:33], v[60:61] op_sel_hi:[1,0]
	v_pk_mul_f32 v[32:33], v[8:9], v[32:33]
	v_pk_mul_f32 v[34:35], v[34:35], v[60:61] op_sel_hi:[1,0]
	v_pk_mul_f32 v[34:35], v[10:11], v[34:35]
	v_pk_mul_f32 v[36:37], v[36:37], v[60:61] op_sel_hi:[1,0]
	v_pk_mul_f32 v[36:37], v[12:13], v[36:37]
	v_pk_mul_f32 v[38:39], v[38:39], v[60:61] op_sel_hi:[1,0]
	v_pk_mul_f32 v[38:39], v[14:15], v[38:39]
	v_pk_mul_f32 v[40:41], v[40:41], v[60:61] op_sel_hi:[1,0]
	v_pk_mul_f32 v[40:41], v[16:17], v[40:41]
	v_pk_mul_f32 v[42:43], v[42:43], v[62:63] op_sel_hi:[1,0]
	v_pk_mul_f32 v[42:43], v[2:3], v[42:43]
	v_pk_mul_f32 v[44:45], v[44:45], v[62:63] op_sel_hi:[1,0]
	v_pk_mul_f32 v[44:45], v[4:5], v[44:45]
	v_pk_mul_f32 v[46:47], v[46:47], v[62:63] op_sel_hi:[1,0]
	v_pk_mul_f32 v[46:47], v[6:7], v[46:47]
	v_pk_mul_f32 v[48:49], v[48:49], v[62:63] op_sel_hi:[1,0]
	v_pk_mul_f32 v[48:49], v[8:9], v[48:49]
	v_pk_mul_f32 v[50:51], v[50:51], v[62:63] op_sel_hi:[1,0]
	v_pk_mul_f32 v[50:51], v[10:11], v[50:51]
	v_pk_mul_f32 v[52:53], v[52:53], v[62:63] op_sel_hi:[1,0]
	v_pk_mul_f32 v[52:53], v[12:13], v[52:53]
	v_pk_mul_f32 v[54:55], v[54:55], v[62:63] op_sel_hi:[1,0]
	v_pk_mul_f32 v[54:55], v[14:15], v[54:55]
	v_pk_mul_f32 v[56:57], v[56:57], v[62:63] op_sel_hi:[1,0]
	v_pk_mul_f32 v[56:57], v[16:17], v[56:57]
	v_cvt_pk_bf16_f32 v26, v26, v27
	v_cvt_pk_bf16_f32 v27, v28, v29
	v_cvt_pk_bf16_f32 v30, v30, v31
	v_cvt_pk_bf16_f32 v31, v32, v33
	v_cvt_pk_bf16_f32 v34, v34, v35
	v_cvt_pk_bf16_f32 v35, v36, v37
	v_cvt_pk_bf16_f32 v38, v38, v39
	v_cvt_pk_bf16_f32 v39, v40, v41
	global_store_dwordx2 v[24:25], v[26:27], off
	global_store_dwordx2 v[24:25], v[30:31], off offset:512
	global_store_dwordx2 v[24:25], v[34:35], off offset:1024
	global_store_dwordx2 v[24:25], v[38:39], off offset:1536
	v_cvt_pk_bf16_f32 v42, v42, v43
	v_cvt_pk_bf16_f32 v43, v44, v45
	v_cvt_pk_bf16_f32 v46, v46, v47
	v_cvt_pk_bf16_f32 v47, v48, v49
	v_cvt_pk_bf16_f32 v50, v50, v51
	v_cvt_pk_bf16_f32 v51, v52, v53
	v_cvt_pk_bf16_f32 v54, v54, v55
	v_cvt_pk_bf16_f32 v55, v56, v57
	global_store_dwordx2 v[58:59], v[42:43], off
	global_store_dwordx2 v[58:59], v[46:47], off offset:512
	global_store_dwordx2 v[58:59], v[50:51], off offset:1024
	global_store_dwordx2 v[58:59], v[54:55], off offset:1536

; __device__ __forceinline__ int ltid() { return launder((int)threadIdx.x); }
; __device__ __forceinline__ void norm_phase(const float* H, const float* g, bf16_t* HN) {
;   const int lane = ltid() & 63, gw = blockIdx.x * 8 + (ltid() >> 6), nw = gridDim.x * 8;
;   f32x4 gv[4];
; #pragma unroll
;   for (int i = 0; i < 4; ++i) gv[i] = *(const f32x4*)(g + lane * 8 + 512 * (i >> 1) + 4 * (i & 1));
;   for (int row = gw; row < NREAL + 64; row += 2 * nw) {
;     const int row2 = row + nw < NREAL + 64 ? row + nw : row;
;     const float* p = H + (size_t)row * DM + lane * 8; const float* p2 = H + (size_t)row2 * DM + lane * 8; f32x4 v[4], u[4]; float ss = 0.f, ss2 = 0.f;
; #pragma unroll
;     for (int i = 0; i < 4; ++i) { v[i] = *(const f32x4*)(p + 512 * (i >> 1) + 4 * (i & 1)); u[i] = *(const f32x4*)(p2 + 512 * (i >> 1) + 4 * (i & 1)); }
; #pragma unroll
.LBB0_1499:
	s_or_b64 exec, exec, s[4:5]
	v_mov_b32_e32 v0, v155
	v_mov_b32_e32 v2, v155
	s_barrier
	v_readlane_b32 s0, v253, 56
	v_ashrrev_i32_e32 v2, 6, v2
	s_nop 0
	v_add_u32_e32 v54, s0, v2
	v_cmp_gt_i32_e32 vcc, s49, v54
	s_and_saveexec_b64 s[6:7], vcc
	v_readlane_b32 s24, v253, 59
	s_cbranch_execz .LBB0_1502
	v_readlane_b32 s0, v254, 54
	v_readlane_b32 s8, v253, 0
	v_readlane_b32 s1, v254, 55
	s_lshl_b32 s90, s0, 10
	v_readlane_b32 s14, v253, 6
	v_readlane_b32 s15, v253, 7
	v_readlane_b32 s18, v253, 10
	v_readlane_b32 s19, v253, 11
	s_lshl_b64 s[0:1], s[90:91], 2
	s_mov_b64 s[14:15], s[18:19]
	v_lshlrev_b32_e32 v0, 2, v0
	s_add_u32 s0, s14, s0
	v_and_b32_e32 v0, 0xfc, v0
	s_addc_u32 s1, s15, s1
	v_lshlrev_b32_e32 v18, 2, v0
	global_load_dwordx4 v[2:5], v18, s[0:1]
	global_load_dwordx4 v[6:9], v18, s[0:1] offset:1024
	global_load_dwordx4 v[10:13], v18, s[0:1] offset:2048
	global_load_dwordx4 v[14:17], v18, s[0:1] offset:3072
	v_readlane_b32 s0, v253, 60
	v_mov_b32_e32 v19, v1
	v_readlane_b32 s1, v253, 61
	v_readlane_b32 s9, v253, 1
	s_mov_b64 s[8:9], 0
	v_lshl_add_u64 v[50:51], s[0:1], 0, v[18:19]
	v_readlane_b32 s0, v253, 62
	v_lshlrev_b32_e32 v18, 1, v0
	v_readlane_b32 s1, v253, 63
	v_readlane_b32 s10, v253, 2
	v_readlane_b32 s11, v253, 3
	v_lshl_add_u64 v[52:53], s[0:1], 0, v[18:19]
	v_readlane_b32 s12, v253, 4
	v_readlane_b32 s13, v253, 5
	v_readlane_b32 s16, v253, 8
	v_readlane_b32 s17, v253, 9
	v_readlane_b32 s20, v253, 12
	v_readlane_b32 s21, v253, 13
	v_readlane_b32 s22, v253, 14
	v_readlane_b32 s23, v253, 15
.LBB0_1501:
	v_readfirstlane_b32 s0, v54
	s_nop 3
	s_add_i32 s9, s0, s24
	s_cmp_lt_i32 s9, s49
	s_cselect_b32 s9, s9, s0
	s_lshl_b32 s10, s0, 12
	s_lshl_b32 s4, s9, 12
	v_mov_b32_e32 v62, s10
	v_mov_b32_e32 v63, 0
	v_lshl_add_u64 v[64:65], v[50:51], 0, v[62:63]
	v_mov_b32_e32 v62, s4
	v_lshl_add_u64 v[66:67], v[50:51], 0, v[62:63]
	global_load_dwordx4 v[18:21], v[64:65], off
	global_load_dwordx4 v[22:25], v[64:65], off offset:1024
	global_load_dwordx4 v[26:29], v[64:65], off offset:2048
	global_load_dwordx4 v[30:33], v[64:65], off offset:3072
	global_load_dwordx4 v[34:37], v[66:67], off
	global_load_dwordx4 v[38:41], v[66:67], off offset:1024
	global_load_dwordx4 v[42:45], v[66:67], off offset:2048
	global_load_dwordx4 v[46:49], v[66:67], off offset:3072
	s_lshl_b32 s10, s0, 11
	s_lshl_b32 s4, s9, 11
	v_mov_b32_e32 v62, s10
	v_lshl_add_u64 v[54:55], v[52:53], 0, v[62:63]
	v_mov_b32_e32 v62, s4
	v_lshl_add_u64 v[56:57], v[52:53], 0, v[62:63]
	s_lshl_b32 s8, s24, 1
	s_add_i32 s1, s0, s8
	s_cmp_lt_i32 s1, s49
	s_cbranch_scc0 .Ln2_lastA_first
	s_add_i32 s9, s1, s24
	s_cmp_lt_i32 s9, s49
	s_cselect_b32 s9, s9, s1
	s_lshl_b32 s10, s1, 12
	s_lshl_b32 s4, s9, 12
	v_mov_b32_e32 v62, s10
	v_mov_b32_e32 v63, 0
	v_lshl_add_u64 v[64:65], v[50:51], 0, v[62:63]
	v_mov_b32_e32 v62, s4
	v_lshl_add_u64 v[66:67], v[50:51], 0, v[62:63]
	global_load_dwordx4 v[70:73], v[64:65], off
	global_load_dwordx4 v[74:77], v[64:65], off offset:1024
	global_load_dwordx4 v[78:81], v[64:65], off offset:2048
	global_load_dwordx4 v[82:85], v[64:65], off offset:3072
	global_load_dwordx4 v[88:91], v[66:67], off
	global_load_dwordx4 v[92:95], v[66:67], off offset:1024
	global_load_dwordx4 v[96:99], v[66:67], off offset:2048
	global_load_dwordx4 v[100:103], v[66:67], off offset:3072
	s_lshl_b32 s10, s1, 11
	s_lshl_b32 s4, s9, 11
	v_mov_b32_e32 v62, s10
	v_lshl_add_u64 v[128:129], v[52:53], 0, v[62:63]
	v_mov_b32_e32 v62, s4
	v_lshl_add_u64 v[130:131], v[52:53], 0, v[62:63]
	s_waitcnt vmcnt(8)
	v_mul_f32_e32 v58, v18, v18
	v_fmac_f32_e32 v58, v19, v19
	v_fmac_f32_e32 v58, v20, v20
	v_fmac_f32_e32 v58, v21, v21
	v_fmac_f32_e32 v58, v22, v22
	v_fmac_f32_e32 v58, v23, v23
	v_fmac_f32_e32 v58, v24, v24
	v_fmac_f32_e32 v58, v25, v25
	v_fmac_f32_e32 v58, v26, v26
	v_fmac_f32_e32 v58, v27, v27
	v_fmac_f32_e32 v58, v28, v28
	v_fmac_f32_e32 v58, v29, v29
	v_fmac_f32_e32 v58, v30, v30
	v_fmac_f32_e32 v58, v31, v31
	v_fmac_f32_e32 v58, v32, v32
	v_fmac_f32_e32 v58, v33, v33
	v_mul_f32_e32 v59, v34, v34
	v_fmac_f32_e32 v59, v35, v35
	v_fmac_f32_e32 v59, v36, v36
	v_fmac_f32_e32 v59, v37, v37
	v_fmac_f32_e32 v59, v38, v38
	v_fmac_f32_e32 v59, v39, v39
	v_fmac_f32_e32 v59, v40, v40
	v_fmac_f32_e32 v59, v41, v41
	v_fmac_f32_e32 v59, v42, v42
	v_fmac_f32_e32 v59, v43, v43
	v_fmac_f32_e32 v59, v44, v44
	v_fmac_f32_e32 v59, v45, v45
	v_fmac_f32_e32 v59, v46, v46
	v_fmac_f32_e32 v59, v47, v47
	v_fmac_f32_e32 v59, v48, v48
	v_fmac_f32_e32 v59, v49, v49
	v_lshlrev_b32_e32 v68, 2, v210
	v_xor_b32_e32 v68, 0x80, v68
	ds_swizzle_b32 v61, v59 offset:swizzle(SWAP,16)
	ds_swizzle_b32 v60, v58 offset:swizzle(SWAP,16)
	s_waitcnt lgkmcnt(0)
	v_pk_add_f32 v[58:59], v[58:59], v[60:61]
	ds_swizzle_b32 v61, v59 offset:swizzle(SWAP,8)
	ds_swizzle_b32 v60, v58 offset:swizzle(SWAP,8)
	s_waitcnt lgkmcnt(0)
	v_pk_add_f32 v[58:59], v[58:59], v[60:61]
	ds_swizzle_b32 v61, v59 offset:swizzle(SWAP,4)
	ds_swizzle_b32 v60, v58 offset:swizzle(SWAP,4)
	s_waitcnt lgkmcnt(0)
	v_pk_add_f32 v[58:59], v[58:59], v[60:61]
	ds_swizzle_b32 v61, v59 offset:swizzle(SWAP,2)
	ds_swizzle_b32 v60, v58 offset:swizzle(SWAP,2)
	s_waitcnt lgkmcnt(0)
	v_pk_add_f32 v[58:59], v[58:59], v[60:61]
	ds_swizzle_b32 v61, v59 offset:swizzle(SWAP,1)
	ds_swizzle_b32 v60, v58 offset:swizzle(SWAP,1)
	s_waitcnt lgkmcnt(0)
	v_pk_add_f32 v[58:59], v[58:59], v[60:61]
	ds_bpermute_b32 v61, v68, v59
	ds_bpermute_b32 v60, v68, v58
	s_waitcnt lgkmcnt(0)
; __device__ __forceinline__ void store8bf(bf16_t* p, f32x4 v0, f32x4 v1) { u32x4 w; w.x = cvt_pk_bf16(v0[0], v0[1]); w.y = cvt_pk_bf16(v0[2], v0[3]); w.z = cvt_pk_bf16(v1[0], v1[1]); w.w = cvt_pk_bf16(v1[2], v1[3]); *(u32x4*)p = w; }
; __device__ __forceinline__ void norm_phase(const float* H, const float* g, bf16_t* HN) {
;     ...
;   for (int row = gw; row < NREAL + 64; row += 2 * nw) {
;     const int row2 = row + nw < NREAL + 64 ? row + nw : row;
;     const float* p = H + (size_t)row * DM + lane * 8; const float* p2 = H + (size_t)row2 * DM + lane * 8; f32x4 v[4], u[4]; float ss = 0.f, ss2 = 0.f;
; #pragma unroll
;     for (int i = 0; i < 4; ++i) { v[i] = *(const f32x4*)(p + 512 * (i >> 1) + 4 * (i & 1)); u[i] = *(const f32x4*)(p2 + 512 * (i >> 1) + 4 * (i & 1)); }
; #pragma unroll
;     for (int i = 0; i < 4; ++i) { ss += v[i][0] * v[i][0] + v[i][1] * v[i][1] + v[i][2] * v[i][2] + v[i][3] * v[i][3]; ss2 += u[i][0] * u[i][0] + u[i][1] * u[i][1] + u[i][2] * u[i][2] + u[i][3] * u[i][3]; }
;     ss = wave_sum(ss); ss2 = wave_sum(ss2); const float rs = rsqrtf(ss * (1.0f / 1024.0f) + 1e-6f), rs2 = rsqrtf(ss2 * (1.0f / 1024.0f) + 1e-6f);
;     bf16_t* q = HN + (size_t)row * DM + lane * 8; bf16_t* q2 = HN + (size_t)row2 * DM + lane * 8;
; #pragma unroll
;     for (int i = 0; i < 2; ++i) { store8bf(q + 512 * i, v[2 * i] * rs * gv[2 * i], v[2 * i + 1] * rs * gv[2 * i + 1]); store8bf(q2 + 512 * i, u[2 * i] * rs2 * gv[2 * i], u[2 * i + 1] * rs2 * gv[2 * i + 1]); }
	v_pk_add_f32 v[58:59], v[58:59], v[60:61]
	s_nop 0
	v_pk_fma_f32 v[58:59], v[58:59], s[58:59], v[154:155] op_sel_hi:[1,0,0]
	s_nop 0
	v_rsq_f32_e32 v58, v58
	v_rsq_f32_e32 v60, v59
	s_nop 0
	v_pk_mul_f32 v[18:19], v[18:19], v[58:59] op_sel_hi:[1,0]
	v_pk_mul_f32 v[18:19], v[2:3], v[18:19]
	v_pk_mul_f32 v[20:21], v[20:21], v[58:59] op_sel_hi:[1,0]
	v_pk_mul_f32 v[20:21], v[4:5], v[20:21]
	v_pk_mul_f32 v[22:23], v[22:23], v[58:59] op_sel_hi:[1,0]
	v_pk_mul_f32 v[22:23], v[6:7], v[22:23]
	v_pk_mul_f32 v[24:25], v[24:25], v[58:59] op_sel_hi:[1,0]
	v_pk_mul_f32 v[24:25], v[8:9], v[24:25]
	v_pk_mul_f32 v[26:27], v[26:27], v[58:59] op_sel_hi:[1,0]
	v_pk_mul_f32 v[26:27], v[10:11], v[26:27]
	v_pk_mul_f32 v[28:29], v[28:29], v[58:59] op_sel_hi:[1,0]
	v_pk_mul_f32 v[28:29], v[12:13], v[28:29]
	v_pk_mul_f32 v[30:31], v[30:31], v[58:59] op_sel_hi:[1,0]
	v_pk_mul_f32 v[30:31], v[14:15], v[30:31]
	v_pk_mul_f32 v[32:33], v[32:33], v[58:59] op_sel_hi:[1,0]
	v_pk_mul_f32 v[32:33], v[16:17], v[32:33]
	v_pk_mul_f32 v[34:35], v[34:35], v[60:61] op_sel_hi:[1,0]
	v_pk_mul_f32 v[34:35], v[2:3], v[34:35]
	v_pk_mul_f32 v[36:37], v[36:37], v[60:61] op_sel_hi:[1,0]
	v_pk_mul_f32 v[36:37], v[4:5], v[36:37]
	v_pk_mul_f32 v[38:39], v[38:39], v[60:61] op_sel_hi:[1,0]
	v_pk_mul_f32 v[38:39], v[6:7], v[38:39]
	v_pk_mul_f32 v[40:41], v[40:41], v[60:61] op_sel_hi:[1,0]
	v_pk_mul_f32 v[40:41], v[8:9], v[40:41]
	v_pk_mul_f32 v[42:43], v[42:43], v[60:61] op_sel_hi:[1,0]
	v_pk_mul_f32 v[42:43], v[10:11], v[42:43]
	v_pk_mul_f32 v[44:45], v[44:45], v[60:61] op_sel_hi:[1,0]
	v_pk_mul_f32 v[44:45], v[12:13], v[44:45]
	v_pk_mul_f32 v[46:47], v[46:47], v[60:61] op_sel_hi:[1,0]
	v_pk_mul_f32 v[46:47], v[14:15], v[46:47]
	v_pk_mul_f32 v[48:49], v[48:49], v[60:61] op_sel_hi:[1,0]
	v_pk_mul_f32 v[48:49], v[16:17], v[48:49]
	v_cvt_pk_bf16_f32 v18, v18, v19
	v_cvt_pk_bf16_f32 v19, v20, v21
	v_cvt_pk_bf16_f32 v22, v22, v23
	v_cvt_pk_bf16_f32 v23, v24, v25
	v_cvt_pk_bf16_f32 v26, v26, v27
	v_cvt_pk_bf16_f32 v27, v28, v29
	v_cvt_pk_bf16_f32 v30, v30, v31
	v_cvt_pk_bf16_f32 v31, v32, v33
	global_store_dwordx2 v[54:55], v[18:19], off
	global_store_dwordx2 v[54:55], v[22:23], off offset:512
	global_store_dwordx2 v[54:55], v[26:27], off offset:1024
	global_store_dwordx2 v[54:55], v[30:31], off offset:1536
	v_cvt_pk_bf16_f32 v34, v34, v35
	v_cvt_pk_bf16_f32 v35, v36, v37
	v_cvt_pk_bf16_f32 v38, v38, v39
	v_cvt_pk_bf16_f32 v39, v40, v41
	v_cvt_pk_bf16_f32 v42, v42, v43
	v_cvt_pk_bf16_f32 v43, v44, v45
	v_cvt_pk_bf16_f32 v46, v46, v47
	v_cvt_pk_bf16_f32 v47, v48, v49
	global_store_dwordx2 v[56:57], v[34:35], off
	global_store_dwordx2 v[56:57], v[38:39], off offset:512
	global_store_dwordx2 v[56:57], v[42:43], off offset:1024
	global_store_dwordx2 v[56:57], v[46:47], off offset:1536
.Ln2_loop:
	s_add_i32 s0, s1, s8
	s_cmp_lt_i32 s0, s49
	s_cbranch_scc0 .Ln2_lastB
	s_add_i32 s9, s0, s24
	s_cmp_lt_i32 s9, s49
	s_cselect_b32 s9, s9, s0
	s_lshl_b32 s10, s0, 12
	s_lshl_b32 s4, s9, 12
	v_mov_b32_e32 v62, s10
	v_mov_b32_e32 v63, 0
	v_lshl_add_u64 v[64:65], v[50:51], 0, v[62:63]
	v_mov_b32_e32 v62, s4
	v_lshl_add_u64 v[66:67], v[50:51], 0, v[62:63]
	global_load_dwordx4 v[18:21], v[64:65], off
	global_load_dwordx4 v[22:25], v[64:65], off offset:1024
	global_load_dwordx4 v[26:29], v[64:65], off offset:2048
	global_load_dwordx4 v[30:33], v[64:65], off offset:3072
	global_load_dwordx4 v[34:37], v[66:67], off
	global_load_dwordx4 v[38:41], v[66:67], off offset:1024
	global_load_dwordx4 v[42:45], v[66:67], off offset:2048
	global_load_dwordx4 v[46:49], v[66:67], off offset:3072
	s_lshl_b32 s10, s0, 11
	s_lshl_b32 s4, s9, 11
	v_mov_b32_e32 v62, s10
	v_lshl_add_u64 v[54:55], v[52:53], 0, v[62:63]
	v_mov_b32_e32 v62, s4
	v_lshl_add_u64 v[56:57], v[52:53], 0, v[62:63]
	s_waitcnt vmcnt(16)
	v_mul_f32_e32 v58, v70, v70
	v_fmac_f32_e32 v58, v71, v71
	v_fmac_f32_e32 v58, v72, v72
	v_fmac_f32_e32 v58, v73, v73
	v_fmac_f32_e32 v58, v74, v74
	v_fmac_f32_e32 v58, v75, v75
	v_fmac_f32_e32 v58, v76, v76
	v_fmac_f32_e32 v58, v77, v77
	v_fmac_f32_e32 v58, v78, v78
	v_fmac_f32_e32 v58, v79, v79
	v_fmac_f32_e32 v58, v80, v80
	v_fmac_f32_e32 v58, v81, v81
	v_fmac_f32_e32 v58, v82, v82
	v_fmac_f32_e32 v58, v83, v83
	v_fmac_f32_e32 v58, v84, v84
	v_fmac_f32_e32 v58, v85, v85
	v_mul_f32_e32 v59, v88, v88
	v_fmac_f32_e32 v59, v89, v89
	v_fmac_f32_e32 v59, v90, v90
	v_fmac_f32_e32 v59, v91, v91
	v_fmac_f32_e32 v59, v92, v92
	v_fmac_f32_e32 v59, v93, v93
	v_fmac_f32_e32 v59, v94, v94
	v_fmac_f32_e32 v59, v95, v95
	v_fmac_f32_e32 v59, v96, v96
	v_fmac_f32_e32 v59, v97, v97
	v_fmac_f32_e32 v59, v98, v98
	v_fmac_f32_e32 v59, v99, v99
	v_fmac_f32_e32 v59, v100, v100
	v_fmac_f32_e32 v59, v101, v101
	v_fmac_f32_e32 v59, v102, v102
	v_fmac_f32_e32 v59, v103, v103
	v_lshlrev_b32_e32 v68, 2, v210
	v_xor_b32_e32 v68, 0x80, v68
	ds_swizzle_b32 v61, v59 offset:swizzle(SWAP,16)
	ds_swizzle_b32 v60, v58 offset:swizzle(SWAP,16)
	s_waitcnt lgkmcnt(0)
	v_pk_add_f32 v[58:59], v[58:59], v[60:61]
	ds_swizzle_b32 v61, v59 offset:swizzle(SWAP,8)
	ds_swizzle_b32 v60, v58 offset:swizzle(SWAP,8)
	s_waitcnt lgkmcnt(0)
	v_pk_add_f32 v[58:59], v[58:59], v[60:61]
	ds_swizzle_b32 v61, v59 offset:swizzle(SWAP,4)
	ds_swizzle_b32 v60, v58 offset:swizzle(SWAP,4)
	s_waitcnt lgkmcnt(0)
	v_pk_add_f32 v[58:59], v[58:59], v[60:61]
	ds_swizzle_b32 v61, v59 offset:swizzle(SWAP,2)
	ds_swizzle_b32 v60, v58 offset:swizzle(SWAP,2)
	s_waitcnt lgkmcnt(0)
	v_pk_add_f32 v[58:59], v[58:59], v[60:61]
	ds_swizzle_b32 v61, v59 offset:swizzle(SWAP,1)
	ds_swizzle_b32 v60, v58 offset:swizzle(SWAP,1)
	s_waitcnt lgkmcnt(0)
	v_pk_add_f32 v[58:59], v[58:59], v[60:61]
	ds_bpermute_b32 v61, v68, v59
	ds_bpermute_b32 v60, v68, v58
	s_waitcnt lgkmcnt(0)
; __device__ __forceinline__ void store8bf(bf16_t* p, f32x4 v0, f32x4 v1) { u32x4 w; w.x = cvt_pk_bf16(v0[0], v0[1]); w.y = cvt_pk_bf16(v0[2], v0[3]); w.z = cvt_pk_bf16(v1[0], v1[1]); w.w = cvt_pk_bf16(v1[2], v1[3]); *(u32x4*)p = w; }
; __device__ __forceinline__ void norm_phase(const float* H, const float* g, bf16_t* HN) {
;     ...
;   for (int row = gw; row < NREAL + 64; row += 2 * nw) {
;     const int row2 = row + nw < NREAL + 64 ? row + nw : row;
;     const float* p = H + (size_t)row * DM + lane * 8; const float* p2 = H + (size_t)row2 * DM + lane * 8; f32x4 v[4], u[4]; float ss = 0.f, ss2 = 0.f;
; #pragma unroll
;     for (int i = 0; i < 4; ++i) { v[i] = *(const f32x4*)(p + 512 * (i >> 1) + 4 * (i & 1)); u[i] = *(const f32x4*)(p2 + 512 * (i >> 1) + 4 * (i & 1)); }
; #pragma unroll
;     for (int i = 0; i < 4; ++i) { ss += v[i][0] * v[i][0] + v[i][1] * v[i][1] + v[i][2] * v[i][2] + v[i][3] * v[i][3]; ss2 += u[i][0] * u[i][0] + u[i][1] * u[i][1] + u[i][2] * u[i][2] + u[i][3] * u[i][3]; }
;     ss = wave_sum(ss); ss2 = wave_sum(ss2); const float rs = rsqrtf(ss * (1.0f / 1024.0f) + 1e-6f), rs2 = rsqrtf(ss2 * (1.0f / 1024.0f) + 1e-6f);
;     bf16_t* q = HN + (size_t)row * DM + lane * 8; bf16_t* q2 = HN + (size_t)row2 * DM + lane * 8;
; #pragma unroll
;     for (int i = 0; i < 2; ++i) { store8bf(q + 512 * i, v[2 * i] * rs * gv[2 * i], v[2 * i + 1] * rs * gv[2 * i + 1]); store8bf(q2 + 512 * i, u[2 * i] * rs2 * gv[2 * i], u[2 * i + 1] * rs2 * gv[2 * i + 1]); }
	v_pk_add_f32 v[58:59], v[58:59], v[60:61]
	s_nop 0
	v_pk_fma_f32 v[58:59], v[58:59], s[58:59], v[154:155] op_sel_hi:[1,0,0]
	s_nop 0
	v_rsq_f32_e32 v58, v58
	v_rsq_f32_e32 v60, v59
	s_nop 0
	v_pk_mul_f32 v[70:71], v[70:71], v[58:59] op_sel_hi:[1,0]
	v_pk_mul_f32 v[70:71], v[2:3], v[70:71]
	v_pk_mul_f32 v[72:73], v[72:73], v[58:59] op_sel_hi:[1,0]
	v_pk_mul_f32 v[72:73], v[4:5], v[72:73]
	v_pk_mul_f32 v[74:75], v[74:75], v[58:59] op_sel_hi:[1,0]
	v_pk_mul_f32 v[74:75], v[6:7], v[74:75]
	v_pk_mul_f32 v[76:77], v[76:77], v[58:59] op_sel_hi:[1,0]
	v_pk_mul_f32 v[76:77], v[8:9], v[76:77]
	v_pk_mul_f32 v[78:79], v[78:79], v[58:59] op_sel_hi:[1,0]
	v_pk_mul_f32 v[78:79], v[10:11], v[78:79]
	v_pk_mul_f32 v[80:81], v[80:81], v[58:59] op_sel_hi:[1,0]
	v_pk_mul_f32 v[80:81], v[12:13], v[80:81]
	v_pk_mul_f32 v[82:83], v[82:83], v[58:59] op_sel_hi:[1,0]
	v_pk_mul_f32 v[82:83], v[14:15], v[82:83]
	v_pk_mul_f32 v[84:85], v[84:85], v[58:59] op_sel_hi:[1,0]
	v_pk_mul_f32 v[84:85], v[16:17], v[84:85]
	v_pk_mul_f32 v[88:89], v[88:89], v[60:61] op_sel_hi:[1,0]
	v_pk_mul_f32 v[88:89], v[2:3], v[88:89]
	v_pk_mul_f32 v[90:91], v[90:91], v[60:61] op_sel_hi:[1,0]
	v_pk_mul_f32 v[90:91], v[4:5], v[90:91]
	v_pk_mul_f32 v[92:93], v[92:93], v[60:61] op_sel_hi:[1,0]
	v_pk_mul_f32 v[92:93], v[6:7], v[92:93]
	v_pk_mul_f32 v[94:95], v[94:95], v[60:61] op_sel_hi:[1,0]
	v_pk_mul_f32 v[94:95], v[8:9], v[94:95]
	v_pk_mul_f32 v[96:97], v[96:97], v[60:61] op_sel_hi:[1,0]
	v_pk_mul_f32 v[96:97], v[10:11], v[96:97]
	v_pk_mul_f32 v[98:99], v[98:99], v[60:61] op_sel_hi:[1,0]
	v_pk_mul_f32 v[98:99], v[12:13], v[98:99]
	v_pk_mul_f32 v[100:101], v[100:101], v[60:61] op_sel_hi:[1,0]
	v_pk_mul_f32 v[100:101], v[14:15], v[100:101]
	v_pk_mul_f32 v[102:103], v[102:103], v[60:61] op_sel_hi:[1,0]
	v_pk_mul_f32 v[102:103], v[16:17], v[102:103]
	v_cvt_pk_bf16_f32 v70, v70, v71
	v_cvt_pk_bf16_f32 v71, v72, v73
	v_cvt_pk_bf16_f32 v74, v74, v75
	v_cvt_pk_bf16_f32 v75, v76, v77
	v_cvt_pk_bf16_f32 v78, v78, v79
	v_cvt_pk_bf16_f32 v79, v80, v81
	v_cvt_pk_bf16_f32 v82, v82, v83
	v_cvt_pk_bf16_f32 v83, v84, v85
	global_store_dwordx2 v[128:129], v[70:71], off
	global_store_dwordx2 v[128:129], v[74:75], off offset:512
	global_store_dwordx2 v[128:129], v[78:79], off offset:1024
	global_store_dwordx2 v[128:129], v[82:83], off offset:1536
	v_cvt_pk_bf16_f32 v88, v88, v89
	v_cvt_pk_bf16_f32 v89, v90, v91
	v_cvt_pk_bf16_f32 v92, v92, v93
	v_cvt_pk_bf16_f32 v93, v94, v95
	v_cvt_pk_bf16_f32 v96, v96, v97
	v_cvt_pk_bf16_f32 v97, v98, v99
	v_cvt_pk_bf16_f32 v100, v100, v101
	v_cvt_pk_bf16_f32 v101, v102, v103
	global_store_dwordx2 v[130:131], v[88:89], off
	global_store_dwordx2 v[130:131], v[92:93], off offset:512
	global_store_dwordx2 v[130:131], v[96:97], off offset:1024
	global_store_dwordx2 v[130:131], v[100:101], off offset:1536
	s_add_i32 s1, s0, s8
	s_cmp_lt_i32 s1, s49
	s_cbranch_scc0 .Ln2_lastA
	s_add_i32 s9, s1, s24
	s_cmp_lt_i32 s9, s49
	s_cselect_b32 s9, s9, s1
	s_lshl_b32 s10, s1, 12
	s_lshl_b32 s4, s9, 12
	v_mov_b32_e32 v62, s10
	v_mov_b32_e32 v63, 0
	v_lshl_add_u64 v[64:65], v[50:51], 0, v[62:63]
	v_mov_b32_e32 v62, s4
	v_lshl_add_u64 v[66:67], v[50:51], 0, v[62:63]
	global_load_dwordx4 v[70:73], v[64:65], off
	global_load_dwordx4 v[74:77], v[64:65], off offset:1024
	global_load_dwordx4 v[78:81], v[64:65], off offset:2048
	global_load_dwordx4 v[82:85], v[64:65], off offset:3072
	global_load_dwordx4 v[88:91], v[66:67], off
	global_load_dwordx4 v[92:95], v[66:67], off offset:1024
	global_load_dwordx4 v[96:99], v[66:67], off offset:2048
	global_load_dwordx4 v[100:103], v[66:67], off offset:3072
	s_lshl_b32 s10, s1, 11
	s_lshl_b32 s4, s9, 11
	v_mov_b32_e32 v62, s10
	v_lshl_add_u64 v[128:129], v[52:53], 0, v[62:63]
	v_mov_b32_e32 v62, s4
	v_lshl_add_u64 v[130:131], v[52:53], 0, v[62:63]
	s_waitcnt vmcnt(16)
	v_mul_f32_e32 v58, v18, v18
	v_fmac_f32_e32 v58, v19, v19
	v_fmac_f32_e32 v58, v20, v20
	v_fmac_f32_e32 v58, v21, v21
	v_fmac_f32_e32 v58, v22, v22
	v_fmac_f32_e32 v58, v23, v23
	v_fmac_f32_e32 v58, v24, v24
	v_fmac_f32_e32 v58, v25, v25
	v_fmac_f32_e32 v58, v26, v26
	v_fmac_f32_e32 v58, v27, v27
	v_fmac_f32_e32 v58, v28, v28
	v_fmac_f32_e32 v58, v29, v29
	v_fmac_f32_e32 v58, v30, v30
	v_fmac_f32_e32 v58, v31, v31
	v_fmac_f32_e32 v58, v32, v32
	v_fmac_f32_e32 v58, v33, v33
	v_mul_f32_e32 v59, v34, v34
	v_fmac_f32_e32 v59, v35, v35
	v_fmac_f32_e32 v59, v36, v36
	v_fmac_f32_e32 v59, v37, v37
	v_fmac_f32_e32 v59, v38, v38
	v_fmac_f32_e32 v59, v39, v39
	v_fmac_f32_e32 v59, v40, v40
	v_fmac_f32_e32 v59, v41, v41
	v_fmac_f32_e32 v59, v42, v42
	v_fmac_f32_e32 v59, v43, v43
	v_fmac_f32_e32 v59, v44, v44
	v_fmac_f32_e32 v59, v45, v45
	v_fmac_f32_e32 v59, v46, v46
	v_fmac_f32_e32 v59, v47, v47
	v_fmac_f32_e32 v59, v48, v48
	v_fmac_f32_e32 v59, v49, v49
	v_lshlrev_b32_e32 v68, 2, v210
	v_xor_b32_e32 v68, 0x80, v68
	ds_swizzle_b32 v61, v59 offset:swizzle(SWAP,16)
	ds_swizzle_b32 v60, v58 offset:swizzle(SWAP,16)
	s_waitcnt lgkmcnt(0)
	v_pk_add_f32 v[58:59], v[58:59], v[60:61]
	ds_swizzle_b32 v61, v59 offset:swizzle(SWAP,8)
	ds_swizzle_b32 v60, v58 offset:swizzle(SWAP,8)
	s_waitcnt lgkmcnt(0)
	v_pk_add_f32 v[58:59], v[58:59], v[60:61]
	ds_swizzle_b32 v61, v59 offset:swizzle(SWAP,4)
	ds_swizzle_b32 v60, v58 offset:swizzle(SWAP,4)
	s_waitcnt lgkmcnt(0)
	v_pk_add_f32 v[58:59], v[58:59], v[60:61]
	ds_swizzle_b32 v61, v59 offset:swizzle(SWAP,2)
	ds_swizzle_b32 v60, v58 offset:swizzle(SWAP,2)
	s_waitcnt lgkmcnt(0)
	v_pk_add_f32 v[58:59], v[58:59], v[60:61]
	ds_swizzle_b32 v61, v59 offset:swizzle(SWAP,1)
	ds_swizzle_b32 v60, v58 offset:swizzle(SWAP,1)
	s_waitcnt lgkmcnt(0)
; __device__ __forceinline__ void store8bf(bf16_t* p, f32x4 v0, f32x4 v1) { u32x4 w; w.x = cvt_pk_bf16(v0[0], v0[1]); w.y = cvt_pk_bf16(v0[2], v0[3]); w.z = cvt_pk_bf16(v1[0], v1[1]); w.w = cvt_pk_bf16(v1[2], v1[3]); *(u32x4*)p = w; }
; __device__ __forceinline__ void norm_phase(const float* H, const float* g, bf16_t* HN) {
;     ...
;   for (int row = gw; row < NREAL + 64; row += 2 * nw) {
;     const int row2 = row + nw < NREAL + 64 ? row + nw : row;
;     const float* p = H + (size_t)row * DM + lane * 8; const float* p2 = H + (size_t)row2 * DM + lane * 8; f32x4 v[4], u[4]; float ss = 0.f, ss2 = 0.f;
; #pragma unroll
;     for (int i = 0; i < 4; ++i) { v[i] = *(const f32x4*)(p + 512 * (i >> 1) + 4 * (i & 1)); u[i] = *(const f32x4*)(p2 + 512 * (i >> 1) + 4 * (i & 1)); }
; #pragma unroll
;     for (int i = 0; i < 4; ++i) { ss += v[i][0] * v[i][0] + v[i][1] * v[i][1] + v[i][2] * v[i][2] + v[i][3] * v[i][3]; ss2 += u[i][0] * u[i][0] + u[i][1] * u[i][1] + u[i][2] * u[i][2] + u[i][3] * u[i][3]; }
;     ss = wave_sum(ss); ss2 = wave_sum(ss2); const float rs = rsqrtf(ss * (1.0f / 1024.0f) + 1e-6f), rs2 = rsqrtf(ss2 * (1.0f / 1024.0f) + 1e-6f);
;     bf16_t* q = HN + (size_t)row * DM + lane * 8; bf16_t* q2 = HN + (size_t)row2 * DM + lane * 8;
; #pragma unroll
;     for (int i = 0; i < 2; ++i) { store8bf(q + 512 * i, v[2 * i] * rs * gv[2 * i], v[2 * i + 1] * rs * gv[2 * i + 1]); store8bf(q2 + 512 * i, u[2 * i] * rs2 * gv[2 * i], u[2 * i + 1] * rs2 * gv[2 * i + 1]); }
	v_pk_add_f32 v[58:59], v[58:59], v[60:61]
	ds_bpermute_b32 v61, v68, v59
	ds_bpermute_b32 v60, v68, v58
	s_waitcnt lgkmcnt(0)
	v_pk_add_f32 v[58:59], v[58:59], v[60:61]
	s_nop 0
	v_pk_fma_f32 v[58:59], v[58:59], s[58:59], v[154:155] op_sel_hi:[1,0,0]
	s_nop 0
	v_rsq_f32_e32 v58, v58
	v_rsq_f32_e32 v60, v59
	s_nop 0
	v_pk_mul_f32 v[18:19], v[18:19], v[58:59] op_sel_hi:[1,0]
	v_pk_mul_f32 v[18:19], v[2:3], v[18:19]
	v_pk_mul_f32 v[20:21], v[20:21], v[58:59] op_sel_hi:[1,0]
	v_pk_mul_f32 v[20:21], v[4:5], v[20:21]
	v_pk_mul_f32 v[22:23], v[22:23], v[58:59] op_sel_hi:[1,0]
	v_pk_mul_f32 v[22:23], v[6:7], v[22:23]
	v_pk_mul_f32 v[24:25], v[24:25], v[58:59] op_sel_hi:[1,0]
	v_pk_mul_f32 v[24:25], v[8:9], v[24:25]
	v_pk_mul_f32 v[26:27], v[26:27], v[58:59] op_sel_hi:[1,0]
	v_pk_mul_f32 v[26:27], v[10:11], v[26:27]
	v_pk_mul_f32 v[28:29], v[28:29], v[58:59] op_sel_hi:[1,0]
	v_pk_mul_f32 v[28:29], v[12:13], v[28:29]
	v_pk_mul_f32 v[30:31], v[30:31], v[58:59] op_sel_hi:[1,0]
	v_pk_mul_f32 v[30:31], v[14:15], v[30:31]
	v_pk_mul_f32 v[32:33], v[32:33], v[58:59] op_sel_hi:[1,0]
	v_pk_mul_f32 v[32:33], v[16:17], v[32:33]
	v_pk_mul_f32 v[34:35], v[34:35], v[60:61] op_sel_hi:[1,0]
	v_pk_mul_f32 v[34:35], v[2:3], v[34:35]
	v_pk_mul_f32 v[36:37], v[36:37], v[60:61] op_sel_hi:[1,0]
	v_pk_mul_f32 v[36:37], v[4:5], v[36:37]
	v_pk_mul_f32 v[38:39], v[38:39], v[60:61] op_sel_hi:[1,0]
	v_pk_mul_f32 v[38:39], v[6:7], v[38:39]
	v_pk_mul_f32 v[40:41], v[40:41], v[60:61] op_sel_hi:[1,0]
	v_pk_mul_f32 v[40:41], v[8:9], v[40:41]
	v_pk_mul_f32 v[42:43], v[42:43], v[60:61] op_sel_hi:[1,0]
	v_pk_mul_f32 v[42:43], v[10:11], v[42:43]
	v_pk_mul_f32 v[44:45], v[44:45], v[60:61] op_sel_hi:[1,0]
	v_pk_mul_f32 v[44:45], v[12:13], v[44:45]
	v_pk_mul_f32 v[46:47], v[46:47], v[60:61] op_sel_hi:[1,0]
	v_pk_mul_f32 v[46:47], v[14:15], v[46:47]
	v_pk_mul_f32 v[48:49], v[48:49], v[60:61] op_sel_hi:[1,0]
	v_pk_mul_f32 v[48:49], v[16:17], v[48:49]
	v_cvt_pk_bf16_f32 v18, v18, v19
	v_cvt_pk_bf16_f32 v19, v20, v21
	v_cvt_pk_bf16_f32 v22, v22, v23
	v_cvt_pk_bf16_f32 v23, v24, v25
	v_cvt_pk_bf16_f32 v26, v26, v27
	v_cvt_pk_bf16_f32 v27, v28, v29
	v_cvt_pk_bf16_f32 v30, v30, v31
	v_cvt_pk_bf16_f32 v31, v32, v33
	global_store_dwordx2 v[54:55], v[18:19], off
	global_store_dwordx2 v[54:55], v[22:23], off offset:512
	global_store_dwordx2 v[54:55], v[26:27], off offset:1024
	global_store_dwordx2 v[54:55], v[30:31], off offset:1536
	v_cvt_pk_bf16_f32 v34, v34, v35
	v_cvt_pk_bf16_f32 v35, v36, v37
	v_cvt_pk_bf16_f32 v38, v38, v39
	v_cvt_pk_bf16_f32 v39, v40, v41
	v_cvt_pk_bf16_f32 v42, v42, v43
	v_cvt_pk_bf16_f32 v43, v44, v45
	v_cvt_pk_bf16_f32 v46, v46, v47
	v_cvt_pk_bf16_f32 v47, v48, v49
	global_store_dwordx2 v[56:57], v[34:35], off
	global_store_dwordx2 v[56:57], v[38:39], off offset:512
	global_store_dwordx2 v[56:57], v[42:43], off offset:1024
	global_store_dwordx2 v[56:57], v[46:47], off offset:1536
	s_branch .Ln2_loop
.Ln2_lastA_first:
	s_waitcnt vmcnt(0)
	v_mul_f32_e32 v58, v18, v18
	v_fmac_f32_e32 v58, v19, v19
	v_fmac_f32_e32 v58, v20, v20
	v_fmac_f32_e32 v58, v21, v21
	v_fmac_f32_e32 v58, v22, v22
	v_fmac_f32_e32 v58, v23, v23
	v_fmac_f32_e32 v58, v24, v24
	v_fmac_f32_e32 v58, v25, v25
	v_fmac_f32_e32 v58, v26, v26
	v_fmac_f32_e32 v58, v27, v27
	v_fmac_f32_e32 v58, v28, v28
	v_fmac_f32_e32 v58, v29, v29
	v_fmac_f32_e32 v58, v30, v30
	v_fmac_f32_e32 v58, v31, v31
	v_fmac_f32_e32 v58, v32, v32
	v_fmac_f32_e32 v58, v33, v33
	v_mul_f32_e32 v59, v34, v34
	v_fmac_f32_e32 v59, v35, v35
	v_fmac_f32_e32 v59, v36, v36
	v_fmac_f32_e32 v59, v37, v37
	v_fmac_f32_e32 v59, v38, v38
	v_fmac_f32_e32 v59, v39, v39
	v_fmac_f32_e32 v59, v40, v40
	v_fmac_f32_e32 v59, v41, v41
	v_fmac_f32_e32 v59, v42, v42
	v_fmac_f32_e32 v59, v43, v43
	v_fmac_f32_e32 v59, v44, v44
	v_fmac_f32_e32 v59, v45, v45
	v_fmac_f32_e32 v59, v46, v46
	v_fmac_f32_e32 v59, v47, v47
	v_fmac_f32_e32 v59, v48, v48
	v_fmac_f32_e32 v59, v49, v49
	v_lshlrev_b32_e32 v68, 2, v210
	v_xor_b32_e32 v68, 0x80, v68
	ds_swizzle_b32 v61, v59 offset:swizzle(SWAP,16)
	ds_swizzle_b32 v60, v58 offset:swizzle(SWAP,16)
	s_waitcnt lgkmcnt(0)
	v_pk_add_f32 v[58:59], v[58:59], v[60:61]
	ds_swizzle_b32 v61, v59 offset:swizzle(SWAP,8)
	ds_swizzle_b32 v60, v58 offset:swizzle(SWAP,8)
	s_waitcnt lgkmcnt(0)
	v_pk_add_f32 v[58:59], v[58:59], v[60:61]
	ds_swizzle_b32 v61, v59 offset:swizzle(SWAP,4)
	ds_swizzle_b32 v60, v58 offset:swizzle(SWAP,4)
	s_waitcnt lgkmcnt(0)
	v_pk_add_f32 v[58:59], v[58:59], v[60:61]
	ds_swizzle_b32 v61, v59 offset:swizzle(SWAP,2)
	ds_swizzle_b32 v60, v58 offset:swizzle(SWAP,2)
	s_waitcnt lgkmcnt(0)
	v_pk_add_f32 v[58:59], v[58:59], v[60:61]
	ds_swizzle_b32 v61, v59 offset:swizzle(SWAP,1)
	ds_swizzle_b32 v60, v58 offset:swizzle(SWAP,1)
	s_waitcnt lgkmcnt(0)
	v_pk_add_f32 v[58:59], v[58:59], v[60:61]
	ds_bpermute_b32 v61, v68, v59
	ds_bpermute_b32 v60, v68, v58
	s_waitcnt lgkmcnt(0)
; __device__ __forceinline__ void store8bf(bf16_t* p, f32x4 v0, f32x4 v1) { u32x4 w; w.x = cvt_pk_bf16(v0[0], v0[1]); w.y = cvt_pk_bf16(v0[2], v0[3]); w.z = cvt_pk_bf16(v1[0], v1[1]); w.w = cvt_pk_bf16(v1[2], v1[3]); *(u32x4*)p = w; }
; __device__ __forceinline__ void norm_phase(const float* H, const float* g, bf16_t* HN) {
;     ...
;   for (int row = gw; row < NREAL + 64; row += 2 * nw) {
;     const int row2 = row + nw < NREAL + 64 ? row + nw : row;
;     const float* p = H + (size_t)row * DM + lane * 8; const float* p2 = H + (size_t)row2 * DM + lane * 8; f32x4 v[4], u[4]; float ss = 0.f, ss2 = 0.f;
; #pragma unroll
;     for (int i = 0; i < 4; ++i) { v[i] = *(const f32x4*)(p + 512 * (i >> 1) + 4 * (i & 1)); u[i] = *(const f32x4*)(p2 + 512 * (i >> 1) + 4 * (i & 1)); }
; #pragma unroll
;     for (int i = 0; i < 4; ++i) { ss += v[i][0] * v[i][0] + v[i][1] * v[i][1] + v[i][2] * v[i][2] + v[i][3] * v[i][3]; ss2 += u[i][0] * u[i][0] + u[i][1] * u[i][1] + u[i][2] * u[i][2] + u[i][3] * u[i][3]; }
;     ss = wave_sum(ss); ss2 = wave_sum(ss2); const float rs = rsqrtf(ss * (1.0f / 1024.0f) + 1e-6f), rs2 = rsqrtf(ss2 * (1.0f / 1024.0f) + 1e-6f);
;     bf16_t* q = HN + (size_t)row * DM + lane * 8; bf16_t* q2 = HN + (size_t)row2 * DM + lane * 8;
; #pragma unroll
;     for (int i = 0; i < 2; ++i) { store8bf(q + 512 * i, v[2 * i] * rs * gv[2 * i], v[2 * i + 1] * rs * gv[2 * i + 1]); store8bf(q2 + 512 * i, u[2 * i] * rs2 * gv[2 * i], u[2 * i + 1] * rs2 * gv[2 * i + 1]); }
	v_pk_add_f32 v[58:59], v[58:59], v[60:61]
	s_nop 0
	v_pk_fma_f32 v[58:59], v[58:59], s[58:59], v[154:155] op_sel_hi:[1,0,0]
	s_nop 0
	v_rsq_f32_e32 v58, v58
	v_rsq_f32_e32 v60, v59
	s_nop 0
	v_pk_mul_f32 v[18:19], v[18:19], v[58:59] op_sel_hi:[1,0]
	v_pk_mul_f32 v[18:19], v[2:3], v[18:19]
	v_pk_mul_f32 v[20:21], v[20:21], v[58:59] op_sel_hi:[1,0]
	v_pk_mul_f32 v[20:21], v[4:5], v[20:21]
	v_pk_mul_f32 v[22:23], v[22:23], v[58:59] op_sel_hi:[1,0]
	v_pk_mul_f32 v[22:23], v[6:7], v[22:23]
	v_pk_mul_f32 v[24:25], v[24:25], v[58:59] op_sel_hi:[1,0]
	v_pk_mul_f32 v[24:25], v[8:9], v[24:25]
	v_pk_mul_f32 v[26:27], v[26:27], v[58:59] op_sel_hi:[1,0]
	v_pk_mul_f32 v[26:27], v[10:11], v[26:27]
	v_pk_mul_f32 v[28:29], v[28:29], v[58:59] op_sel_hi:[1,0]
	v_pk_mul_f32 v[28:29], v[12:13], v[28:29]
	v_pk_mul_f32 v[30:31], v[30:31], v[58:59] op_sel_hi:[1,0]
	v_pk_mul_f32 v[30:31], v[14:15], v[30:31]
	v_pk_mul_f32 v[32:33], v[32:33], v[58:59] op_sel_hi:[1,0]
	v_pk_mul_f32 v[32:33], v[16:17], v[32:33]
	v_pk_mul_f32 v[34:35], v[34:35], v[60:61] op_sel_hi:[1,0]
	v_pk_mul_f32 v[34:35], v[2:3], v[34:35]
	v_pk_mul_f32 v[36:37], v[36:37], v[60:61] op_sel_hi:[1,0]
	v_pk_mul_f32 v[36:37], v[4:5], v[36:37]
	v_pk_mul_f32 v[38:39], v[38:39], v[60:61] op_sel_hi:[1,0]
	v_pk_mul_f32 v[38:39], v[6:7], v[38:39]
	v_pk_mul_f32 v[40:41], v[40:41], v[60:61] op_sel_hi:[1,0]
	v_pk_mul_f32 v[40:41], v[8:9], v[40:41]
	v_pk_mul_f32 v[42:43], v[42:43], v[60:61] op_sel_hi:[1,0]
	v_pk_mul_f32 v[42:43], v[10:11], v[42:43]
	v_pk_mul_f32 v[44:45], v[44:45], v[60:61] op_sel_hi:[1,0]
	v_pk_mul_f32 v[44:45], v[12:13], v[44:45]
	v_pk_mul_f32 v[46:47], v[46:47], v[60:61] op_sel_hi:[1,0]
	v_pk_mul_f32 v[46:47], v[14:15], v[46:47]
	v_pk_mul_f32 v[48:49], v[48:49], v[60:61] op_sel_hi:[1,0]
	v_pk_mul_f32 v[48:49], v[16:17], v[48:49]
	v_cvt_pk_bf16_f32 v18, v18, v19
	v_cvt_pk_bf16_f32 v19, v20, v21
	v_cvt_pk_bf16_f32 v22, v22, v23
	v_cvt_pk_bf16_f32 v23, v24, v25
	v_cvt_pk_bf16_f32 v26, v26, v27
	v_cvt_pk_bf16_f32 v27, v28, v29
	v_cvt_pk_bf16_f32 v30, v30, v31
	v_cvt_pk_bf16_f32 v31, v32, v33
	global_store_dwordx2 v[54:55], v[18:19], off
	global_store_dwordx2 v[54:55], v[22:23], off offset:512
	global_store_dwordx2 v[54:55], v[26:27], off offset:1024
	global_store_dwordx2 v[54:55], v[30:31], off offset:1536
	v_cvt_pk_bf16_f32 v34, v34, v35
	v_cvt_pk_bf16_f32 v35, v36, v37
	v_cvt_pk_bf16_f32 v38, v38, v39
	v_cvt_pk_bf16_f32 v39, v40, v41
	v_cvt_pk_bf16_f32 v42, v42, v43
	v_cvt_pk_bf16_f32 v43, v44, v45
	v_cvt_pk_bf16_f32 v46, v46, v47
	v_cvt_pk_bf16_f32 v47, v48, v49
	global_store_dwordx2 v[56:57], v[34:35], off
	global_store_dwordx2 v[56:57], v[38:39], off offset:512
	global_store_dwordx2 v[56:57], v[42:43], off offset:1024
	global_store_dwordx2 v[56:57], v[46:47], off offset:1536
	s_branch .Ln2_done
.Ln2_lastB:
	s_waitcnt vmcnt(0)
	v_mul_f32_e32 v58, v70, v70
	v_fmac_f32_e32 v58, v71, v71
	v_fmac_f32_e32 v58, v72, v72
	v_fmac_f32_e32 v58, v73, v73
	v_fmac_f32_e32 v58, v74, v74
	v_fmac_f32_e32 v58, v75, v75
	v_fmac_f32_e32 v58, v76, v76
	v_fmac_f32_e32 v58, v77, v77
	v_fmac_f32_e32 v58, v78, v78
	v_fmac_f32_e32 v58, v79, v79
	v_fmac_f32_e32 v58, v80, v80
	v_fmac_f32_e32 v58, v81, v81
	v_fmac_f32_e32 v58, v82, v82
	v_fmac_f32_e32 v58, v83, v83
	v_fmac_f32_e32 v58, v84, v84
	v_fmac_f32_e32 v58, v85, v85
	v_mul_f32_e32 v59, v88, v88
	v_fmac_f32_e32 v59, v89, v89
	v_fmac_f32_e32 v59, v90, v90
	v_fmac_f32_e32 v59, v91, v91
	v_fmac_f32_e32 v59, v92, v92
	v_fmac_f32_e32 v59, v93, v93
	v_fmac_f32_e32 v59, v94, v94
	v_fmac_f32_e32 v59, v95, v95
	v_fmac_f32_e32 v59, v96, v96
	v_fmac_f32_e32 v59, v97, v97
	v_fmac_f32_e32 v59, v98, v98
	v_fmac_f32_e32 v59, v99, v99
	v_fmac_f32_e32 v59, v100, v100
	v_fmac_f32_e32 v59, v101, v101
	v_fmac_f32_e32 v59, v102, v102
	v_fmac_f32_e32 v59, v103, v103
	v_lshlrev_b32_e32 v68, 2, v210
	v_xor_b32_e32 v68, 0x80, v68
	ds_swizzle_b32 v61, v59 offset:swizzle(SWAP,16)
	ds_swizzle_b32 v60, v58 offset:swizzle(SWAP,16)
	s_waitcnt lgkmcnt(0)
	v_pk_add_f32 v[58:59], v[58:59], v[60:61]
	ds_swizzle_b32 v61, v59 offset:swizzle(SWAP,8)
	ds_swizzle_b32 v60, v58 offset:swizzle(SWAP,8)
	s_waitcnt lgkmcnt(0)
	v_pk_add_f32 v[58:59], v[58:59], v[60:61]
	ds_swizzle_b32 v61, v59 offset:swizzle(SWAP,4)
	ds_swizzle_b32 v60, v58 offset:swizzle(SWAP,4)
	s_waitcnt lgkmcnt(0)
	v_pk_add_f32 v[58:59], v[58:59], v[60:61]
	ds_swizzle_b32 v61, v59 offset:swizzle(SWAP,2)
	ds_swizzle_b32 v60, v58 offset:swizzle(SWAP,2)
	s_waitcnt lgkmcnt(0)
	v_pk_add_f32 v[58:59], v[58:59], v[60:61]
	ds_swizzle_b32 v61, v59 offset:swizzle(SWAP,1)
	ds_swizzle_b32 v60, v58 offset:swizzle(SWAP,1)
	s_waitcnt lgkmcnt(0)
	v_pk_add_f32 v[58:59], v[58:59], v[60:61]
	ds_bpermute_b32 v61, v68, v59
	ds_bpermute_b32 v60, v68, v58
	s_waitcnt lgkmcnt(0)
; __device__ __forceinline__ void store8bf(bf16_t* p, f32x4 v0, f32x4 v1) { u32x4 w; w.x = cvt_pk_bf16(v0[0], v0[1]); w.y = cvt_pk_bf16(v0[2], v0[3]); w.z = cvt_pk_bf16(v1[0], v1[1]); w.w = cvt_pk_bf16(v1[2], v1[3]); *(u32x4*)p = w; }
; __device__ __forceinline__ void norm_phase(const float* H, const float* g, bf16_t* HN) {
;     ...
;     for (int i = 0; i < 4; ++i) { ss += v[i][0] * v[i][0] + v[i][1] * v[i][1] + v[i][2] * v[i][2] + v[i][3] * v[i][3]; ss2 += u[i][0] * u[i][0] + u[i][1] * u[i][1] + u[i][2] * u[i][2] + u[i][3] * u[i][3]; }
;     ss = wave_sum(ss); ss2 = wave_sum(ss2); const float rs = rsqrtf(ss * (1.0f / 1024.0f) + 1e-6f), rs2 = rsqrtf(ss2 * (1.0f / 1024.0f) + 1e-6f);
;     bf16_t* q = HN + (size_t)row * DM + lane * 8; bf16_t* q2 = HN + (size_t)row2 * DM + lane * 8;
; #pragma unroll
;     for (int i = 0; i < 2; ++i) { store8bf(q + 512 * i, v[2 * i] * rs * gv[2 * i], v[2 * i + 1] * rs * gv[2 * i + 1]); store8bf(q2 + 512 * i, u[2 * i] * rs2 * gv[2 * i], u[2 * i + 1] * rs2 * gv[2 * i + 1]); }
	v_pk_add_f32 v[58:59], v[58:59], v[60:61]
	s_nop 0
	v_pk_fma_f32 v[58:59], v[58:59], s[58:59], v[154:155] op_sel_hi:[1,0,0]
	s_nop 0
	v_rsq_f32_e32 v58, v58
	v_rsq_f32_e32 v60, v59
	s_nop 0
	v_pk_mul_f32 v[70:71], v[70:71], v[58:59] op_sel_hi:[1,0]
	v_pk_mul_f32 v[70:71], v[2:3], v[70:71]
	v_pk_mul_f32 v[72:73], v[72:73], v[58:59] op_sel_hi:[1,0]
	v_pk_mul_f32 v[72:73], v[4:5], v[72:73]
	v_pk_mul_f32 v[74:75], v[74:75], v[58:59] op_sel_hi:[1,0]
	v_pk_mul_f32 v[74:75], v[6:7], v[74:75]
	v_pk_mul_f32 v[76:77], v[76:77], v[58:59] op_sel_hi:[1,0]
	v_pk_mul_f32 v[76:77], v[8:9], v[76:77]
	v_pk_mul_f32 v[78:79], v[78:79], v[58:59] op_sel_hi:[1,0]
	v_pk_mul_f32 v[78:79], v[10:11], v[78:79]
	v_pk_mul_f32 v[80:81], v[80:81], v[58:59] op_sel_hi:[1,0]
	v_pk_mul_f32 v[80:81], v[12:13], v[80:81]
	v_pk_mul_f32 v[82:83], v[82:83], v[58:59] op_sel_hi:[1,0]
	v_pk_mul_f32 v[82:83], v[14:15], v[82:83]
	v_pk_mul_f32 v[84:85], v[84:85], v[58:59] op_sel_hi:[1,0]
	v_pk_mul_f32 v[84:85], v[16:17], v[84:85]
	v_pk_mul_f32 v[88:89], v[88:89], v[60:61] op_sel_hi:[1,0]
	v_pk_mul_f32 v[88:89], v[2:3], v[88:89]
	v_pk_mul_f32 v[90:91], v[90:91], v[60:61] op_sel_hi:[1,0]
	v_pk_mul_f32 v[90:91], v[4:5], v[90:91]
	v_pk_mul_f32 v[92:93], v[92:93], v[60:61] op_sel_hi:[1,0]
	v_pk_mul_f32 v[92:93], v[6:7], v[92:93]
	v_pk_mul_f32 v[94:95], v[94:95], v[60:61] op_sel_hi:[1,0]
	v_pk_mul_f32 v[94:95], v[8:9], v[94:95]
	v_pk_mul_f32 v[96:97], v[96:97], v[60:61] op_sel_hi:[1,0]
	v_pk_mul_f32 v[96:97], v[10:11], v[96:97]
	v_pk_mul_f32 v[98:99], v[98:99], v[60:61] op_sel_hi:[1,0]
	v_pk_mul_f32 v[98:99], v[12:13], v[98:99]
	v_pk_mul_f32 v[100:101], v[100:101], v[60:61] op_sel_hi:[1,0]
	v_pk_mul_f32 v[100:101], v[14:15], v[100:101]
	v_pk_mul_f32 v[102:103], v[102:103], v[60:61] op_sel_hi:[1,0]
	v_pk_mul_f32 v[102:103], v[16:17], v[102:103]
	v_cvt_pk_bf16_f32 v70, v70, v71
	v_cvt_pk_bf16_f32 v71, v72, v73
	v_cvt_pk_bf16_f32 v74, v74, v75
	v_cvt_pk_bf16_f32 v75, v76, v77
	v_cvt_pk_bf16_f32 v78, v78, v79
	v_cvt_pk_bf16_f32 v79, v80, v81
	v_cvt_pk_bf16_f32 v82, v82, v83
	v_cvt_pk_bf16_f32 v83, v84, v85
	global_store_dwordx2 v[128:129], v[70:71], off
	global_store_dwordx2 v[128:129], v[74:75], off offset:512
	global_store_dwordx2 v[128:129], v[78:79], off offset:1024
	global_store_dwordx2 v[128:129], v[82:83], off offset:1536
	v_cvt_pk_bf16_f32 v88, v88, v89
	v_cvt_pk_bf16_f32 v89, v90, v91
	v_cvt_pk_bf16_f32 v92, v92, v93
	v_cvt_pk_bf16_f32 v93, v94, v95
	v_cvt_pk_bf16_f32 v96, v96, v97
	v_cvt_pk_bf16_f32 v97, v98, v99
	v_cvt_pk_bf16_f32 v100, v100, v101
	v_cvt_pk_bf16_f32 v101, v102, v103
	global_store_dwordx2 v[130:131], v[88:89], off
	global_store_dwordx2 v[130:131], v[92:93], off offset:512
	global_store_dwordx2 v[130:131], v[96:97], off offset:1024
	global_store_dwordx2 v[130:131], v[100:101], off offset:1536
	s_branch .Ln2_done
; __device__ __forceinline__ void store8bf(bf16_t* p, f32x4 v0, f32x4 v1) { u32x4 w; w.x = cvt_pk_bf16(v0[0], v0[1]); w.y = cvt_pk_bf16(v0[2], v0[3]); w.z = cvt_pk_bf16(v1[0], v1[1]); w.w = cvt_pk_bf16(v1[2], v1[3]); *(u32x4*)p = w; }
; __device__ __forceinline__ void norm_phase(const float* H, const float* g, bf16_t* HN) {
;     ...
;   for (int row = gw; row < NREAL + 64; row += 2 * nw) {
;     const int row2 = row + nw < NREAL + 64 ? row + nw : row;
;     const float* p = H + (size_t)row * DM + lane * 8; const float* p2 = H + (size_t)row2 * DM + lane * 8; f32x4 v[4], u[4]; float ss = 0.f, ss2 = 0.f;
; #pragma unroll
;     for (int i = 0; i < 4; ++i) { v[i] = *(const f32x4*)(p + 512 * (i >> 1) + 4 * (i & 1)); u[i] = *(const f32x4*)(p2 + 512 * (i >> 1) + 4 * (i & 1)); }
; #pragma unroll
;     for (int i = 0; i < 4; ++i) { ss += v[i][0] * v[i][0] + v[i][1] * v[i][1] + v[i][2] * v[i][2] + v[i][3] * v[i][3]; ss2 += u[i][0] * u[i][0] + u[i][1] * u[i][1] + u[i][2] * u[i][2] + u[i][3] * u[i][3]; }
;     ss = wave_sum(ss); ss2 = wave_sum(ss2); const float rs = rsqrtf(ss * (1.0f / 1024.0f) + 1e-6f), rs2 = rsqrtf(ss2 * (1.0f / 1024.0f) + 1e-6f);
;     bf16_t* q = HN + (size_t)row * DM + lane * 8; bf16_t* q2 = HN + (size_t)row2 * DM + lane * 8;
; #pragma unroll
;     for (int i = 0; i < 2; ++i) { store8bf(q + 512 * i, v[2 * i] * rs * gv[2 * i], v[2 * i + 1] * rs * gv[2 * i + 1]); store8bf(q2 + 512 * i, u[2 * i] * rs2 * gv[2 * i], u[2 * i + 1] * rs2 * gv[2 * i + 1]); }
.Ln2_lastA:
	s_waitcnt vmcnt(0)
	v_mul_f32_e32 v58, v18, v18
	v_fmac_f32_e32 v58, v19, v19
	v_fmac_f32_e32 v58, v20, v20
	v_fmac_f32_e32 v58, v21, v21
	v_fmac_f32_e32 v58, v22, v22
	v_fmac_f32_e32 v58, v23, v23
	v_fmac_f32_e32 v58, v24, v24
	v_fmac_f32_e32 v58, v25, v25
	v_fmac_f32_e32 v58, v26, v26
	v_fmac_f32_e32 v58, v27, v27
	v_fmac_f32_e32 v58, v28, v28
	v_fmac_f32_e32 v58, v29, v29
	v_fmac_f32_e32 v58, v30, v30
	v_fmac_f32_e32 v58, v31, v31
	v_fmac_f32_e32 v58, v32, v32
	v_fmac_f32_e32 v58, v33, v33
	v_mul_f32_e32 v59, v34, v34
	v_fmac_f32_e32 v59, v35, v35
	v_fmac_f32_e32 v59, v36, v36
	v_fmac_f32_e32 v59, v37, v37
	v_fmac_f32_e32 v59, v38, v38
	v_fmac_f32_e32 v59, v39, v39
	v_fmac_f32_e32 v59, v40, v40
	v_fmac_f32_e32 v59, v41, v41
	v_fmac_f32_e32 v59, v42, v42
	v_fmac_f32_e32 v59, v43, v43
	v_fmac_f32_e32 v59, v44, v44
	v_fmac_f32_e32 v59, v45, v45
	v_fmac_f32_e32 v59, v46, v46
	v_fmac_f32_e32 v59, v47, v47
	v_fmac_f32_e32 v59, v48, v48
	v_fmac_f32_e32 v59, v49, v49
	v_lshlrev_b32_e32 v68, 2, v210
	v_xor_b32_e32 v68, 0x80, v68
	ds_swizzle_b32 v61, v59 offset:swizzle(SWAP,16)
	ds_swizzle_b32 v60, v58 offset:swizzle(SWAP,16)
	s_waitcnt lgkmcnt(0)
	v_pk_add_f32 v[58:59], v[58:59], v[60:61]
	ds_swizzle_b32 v61, v59 offset:swizzle(SWAP,8)
	ds_swizzle_b32 v60, v58 offset:swizzle(SWAP,8)
	s_waitcnt lgkmcnt(0)
	v_pk_add_f32 v[58:59], v[58:59], v[60:61]
	ds_swizzle_b32 v61, v59 offset:swizzle(SWAP,4)
	ds_swizzle_b32 v60, v58 offset:swizzle(SWAP,4)
	s_waitcnt lgkmcnt(0)
	v_pk_add_f32 v[58:59], v[58:59], v[60:61]
	ds_swizzle_b32 v61, v59 offset:swizzle(SWAP,2)
	ds_swizzle_b32 v60, v58 offset:swizzle(SWAP,2)
	s_waitcnt lgkmcnt(0)
	v_pk_add_f32 v[58:59], v[58:59], v[60:61]
	ds_swizzle_b32 v61, v59 offset:swizzle(SWAP,1)
	ds_swizzle_b32 v60, v58 offset:swizzle(SWAP,1)
	s_waitcnt lgkmcnt(0)
	v_pk_add_f32 v[58:59], v[58:59], v[60:61]
	ds_bpermute_b32 v61, v68, v59
	ds_bpermute_b32 v60, v68, v58
	s_waitcnt lgkmcnt(0)
	v_pk_add_f32 v[58:59], v[58:59], v[60:61]
	s_nop 0
	v_pk_fma_f32 v[58:59], v[58:59], s[58:59], v[154:155] op_sel_hi:[1,0,0]
	s_nop 0
	v_rsq_f32_e32 v58, v58
	v_rsq_f32_e32 v60, v59
	s_nop 0
	v_pk_mul_f32 v[18:19], v[18:19], v[58:59] op_sel_hi:[1,0]
	v_pk_mul_f32 v[18:19], v[2:3], v[18:19]
	v_pk_mul_f32 v[20:21], v[20:21], v[58:59] op_sel_hi:[1,0]
	v_pk_mul_f32 v[20:21], v[4:5], v[20:21]
	v_pk_mul_f32 v[22:23], v[22:23], v[58:59] op_sel_hi:[1,0]
	v_pk_mul_f32 v[22:23], v[6:7], v[22:23]
	v_pk_mul_f32 v[24:25], v[24:25], v[58:59] op_sel_hi:[1,0]
	v_pk_mul_f32 v[24:25], v[8:9], v[24:25]
	v_pk_mul_f32 v[26:27], v[26:27], v[58:59] op_sel_hi:[1,0]
	v_pk_mul_f32 v[26:27], v[10:11], v[26:27]
	v_pk_mul_f32 v[28:29], v[28:29], v[58:59] op_sel_hi:[1,0]
	v_pk_mul_f32 v[28:29], v[12:13], v[28:29]
	v_pk_mul_f32 v[30:31], v[30:31], v[58:59] op_sel_hi:[1,0]
	v_pk_mul_f32 v[30:31], v[14:15], v[30:31]
	v_pk_mul_f32 v[32:33], v[32:33], v[58:59] op_sel_hi:[1,0]
	v_pk_mul_f32 v[32:33], v[16:17], v[32:33]
	v_pk_mul_f32 v[34:35], v[34:35], v[60:61] op_sel_hi:[1,0]
	v_pk_mul_f32 v[34:35], v[2:3], v[34:35]
	v_pk_mul_f32 v[36:37], v[36:37], v[60:61] op_sel_hi:[1,0]
	v_pk_mul_f32 v[36:37], v[4:5], v[36:37]
	v_pk_mul_f32 v[38:39], v[38:39], v[60:61] op_sel_hi:[1,0]
	v_pk_mul_f32 v[38:39], v[6:7], v[38:39]
	v_pk_mul_f32 v[40:41], v[40:41], v[60:61] op_sel_hi:[1,0]
	v_pk_mul_f32 v[40:41], v[8:9], v[40:41]
	v_pk_mul_f32 v[42:43], v[42:43], v[60:61] op_sel_hi:[1,0]
	v_pk_mul_f32 v[42:43], v[10:11], v[42:43]
	v_pk_mul_f32 v[44:45], v[44:45], v[60:61] op_sel_hi:[1,0]
	v_pk_mul_f32 v[44:45], v[12:13], v[44:45]
	v_pk_mul_f32 v[46:47], v[46:47], v[60:61] op_sel_hi:[1,0]
	v_pk_mul_f32 v[46:47], v[14:15], v[46:47]
	v_pk_mul_f32 v[48:49], v[48:49], v[60:61] op_sel_hi:[1,0]
	v_pk_mul_f32 v[48:49], v[16:17], v[48:49]
	v_cvt_pk_bf16_f32 v18, v18, v19
	v_cvt_pk_bf16_f32 v19, v20, v21
	v_cvt_pk_bf16_f32 v22, v22, v23
	v_cvt_pk_bf16_f32 v23, v24, v25
	v_cvt_pk_bf16_f32 v26, v26, v27
	v_cvt_pk_bf16_f32 v27, v28, v29
	v_cvt_pk_bf16_f32 v30, v30, v31
	v_cvt_pk_bf16_f32 v31, v32, v33
	global_store_dwordx2 v[54:55], v[18:19], off
	global_store_dwordx2 v[54:55], v[22:23], off offset:512
	global_store_dwordx2 v[54:55], v[26:27], off offset:1024
	global_store_dwordx2 v[54:55], v[30:31], off offset:1536
	v_cvt_pk_bf16_f32 v34, v34, v35
	v_cvt_pk_bf16_f32 v35, v36, v37
	v_cvt_pk_bf16_f32 v38, v38, v39
	v_cvt_pk_bf16_f32 v39, v40, v41
	v_cvt_pk_bf16_f32 v42, v42, v43
	v_cvt_pk_bf16_f32 v43, v44, v45
	v_cvt_pk_bf16_f32 v46, v46, v47
	v_cvt_pk_bf16_f32 v47, v48, v49
	global_store_dwordx2 v[56:57], v[34:35], off
	global_store_dwordx2 v[56:57], v[38:39], off offset:512
	global_store_dwordx2 v[56:57], v[42:43], off offset:1024
	global_store_dwordx2 v[56:57], v[46:47], off offset:1536
